# v47 + removed 127 dead zero-initialisers preceding full-mask row_ror DPP moves in GEMM4 conv epilogue
# speedup vs baseline: 1.0011x; 1.0011x over previous
; #define PG8_LAS __attribute__((address_space(3)))
;     __device__ __forceinline__ void run(const f32x4 (&acc)[2][2][4][2], const Unit& u, int wr, int wc, int fr, int fq, PG8_LAS unsigned char* lds, int buf) const {
;         const int row0 = u.pm * BM + wr * 64 + fr, ch0 = u.pn * 128 + wc * 32 + 8 * fq;
;         const PG8_LAS float* vl = (const PG8_LAS float*)(lds + EPI_LDS_OFF + buf * 2048) + wc * 32 + 8 * fq;
;         const int lane = fq * 16 + fr, lup = (lane & 48) | ((lane - 1) & 15), ldn = (lane & 48) | ((lane + 1) & 15);
;         f32x4 w0[2], w1[2], w2[2], bb[2];
; #pragma unroll
;         for (int n = 0; n < 2; ++n) { w0[n] = *(const PG8_LAS f32x4*)(vl + 4 * n); w1[n] = *(const PG8_LAS f32x4*)(vl + 128 + 4 * n); w2[n] = *(const PG8_LAS f32x4*)(vl + 256 + 4 * n); bb[n] = *(const PG8_LAS f32x4*)(vl + 384 + 4 * n); }
; #pragma unroll
;         for (int ai = 0; ai < 2; ++ai) {
;             unsigned op[4][2][2];
; #pragma unroll
;             for (int n = 0; n < 2; ++n)
; #pragma unroll
;                 for (int ep = 0; ep < 2; ++ep) {
;                     float ov[4][2], xv[4][2];
; #pragma unroll
;                     for (int eh = 0; eh < 2; ++eh) { const int e = 2 * ep + eh;
;                         float R[4], L[4];
; #pragma unroll
;                         for (int m = 0; m < 4; ++m) { R[m] = dpp_ror<1>(acc[ai][1][m][n][e]); L[m] = dpp_ror<15>(acc[ai][1][m][n][e]); }
; #pragma unroll
;                         for (int m = 0; m < 4; ++m) {
;                             const float up = (fr == 0) ? R[m > 0 ? m - 1 : 0] : R[m];
;                             const float dn = (fr == 15) ? L[m < 3 ? m + 1 : 3] : L[m];
;                             xv[m][eh] = up * w0[n][e] + acc[ai][1][m][n][e] * w1[n][e] + dn * w2[n][e] + bb[n][e];
;                         } }
; #pragma unroll
;                     for (int m = 0; m < 4; ++m) {
;                         const float p0 = __builtin_amdgcn_exp2f(fminf(-1.4426950408889634f * xv[m][0], 60.0f)) + 1.0f, p1 = __builtin_amdgcn_exp2f(fminf(-1.4426950408889634f * xv[m][1], 60.0f)) + 1.0f;
;                         const float r = __builtin_amdgcn_rcpf(p0 * p1);
;                         const bool edge = (m == 0 && fr == 0) || (m == 3 && fr == 15);
;                         ov[m][0] = edge ? acc[ai][0][m][n][2 * ep] : xv[m][0] * (r * p1) * acc[ai][0][m][n][2 * ep];
.LBB0_1162:
	s_lshl_b32 s23, s23, 11
	s_and_b32 s23, s23, 0x800
	v_add_u32_e32 v70, s23, v179
	v_mov_b32_dpp v195, v94 row_ror:15 row_mask:0xf bank_mask:0xf
	v_mov_b32_dpp v202, v158 row_ror:15 row_mask:0xf bank_mask:0xf
	v_cmp_ne_u64_e32 vcc, 0, v[170:171]
	ds_read_b128 v[122:125], v70
	ds_read_b128 v[66:69], v70 offset:16
	ds_read_b128 v[126:129], v70 offset:512
	ds_read_b128 v[74:77], v70 offset:528
	ds_read_b128 v[134:137], v70 offset:1024
	ds_read_b128 v[78:81], v70 offset:1040
	ds_read_b128 v[130:133], v70 offset:1536
	ds_read_b128 v[70:73], v70 offset:1552
	v_mov_b32_dpp v204, v154 row_ror:15 row_mask:0xf bank_mask:0xf
	v_cndmask_b32_e32 v191, v195, v202, vcc
	v_cmp_eq_u32_e64 s[48:49], 2, v170
	v_mov_b32_dpp v196, v86 row_ror:15 row_mask:0xf bank_mask:0xf
	v_cmp_eq_u32_e64 s[50:51], 3, v170
	v_cndmask_b32_e64 v191, v191, v204, s[48:49]
	v_cndmask_b32_e64 v199, v191, v196, s[50:51]
	v_mov_b32_e32 v200, v94
	s_waitcnt lgkmcnt(0)
	v_mov_b32_e32 v201, v134
	v_mov_b32_e32 v198, v126
	v_mov_b32_dpp v190, v94 row_ror:1 row_mask:0xf bank_mask:0xf
	v_pk_mul_f32 v[198:199], v[200:201], v[198:199]
	v_fma_f32 v198, v122, v190, v198
	v_mov_b32_dpp v197, v158 row_ror:1 row_mask:0xf bank_mask:0xf
	v_add_f32_e32 v198, v198, v199
	v_cmp_ne_u64_e64 s[52:53], 0, v[172:173]
	v_mov_b32_dpp v203, v154 row_ror:1 row_mask:0xf bank_mask:0xf
	v_add_f32_e32 v207, v130, v198
	v_cndmask_b32_e64 v198, v190, v197, s[52:53]
	v_cmp_eq_u32_e64 s[54:55], 2, v172
	v_lshl_add_u32 v194, s56, 8, v175
	v_lshl_or_b32 v188, s57, 7, v192
	s_lshl_b32 s23, s56, 2
	v_mov_b32_dpp v205, v86 row_ror:1 row_mask:0xf bank_mask:0xf
	v_cndmask_b32_e64 v198, v198, v203, s[54:55]
	v_cmp_eq_u32_e64 s[56:57], 3, v172
	v_cmp_eq_u32_e64 s[58:59], 1, v174
	v_cmp_eq_u32_e64 s[60:61], 2, v174
	v_cndmask_b32_e64 v208, v198, v205, s[56:57]
	v_cndmask_b32_e64 v198, v195, v202, s[58:59]
	v_cndmask_b32_e64 v198, v198, v204, s[60:61]
	v_cmp_eq_u32_e64 s[62:63], 3, v174
	v_mov_b32_e32 v200, v158
	v_cmp_eq_u32_e64 s[70:71], 1, v178
	v_cndmask_b32_e64 v199, v198, v196, s[62:63]
	v_mov_b32_e32 v198, v126
	v_pk_mul_f32 v[198:199], v[200:201], v[198:199]
	v_cmp_eq_u32_e64 s[64:65], 1, v176
	v_fma_f32 v158, v122, v208, v198
	v_add_f32_e32 v158, v158, v199
	v_cndmask_b32_e64 v195, v195, v202, s[70:71]
	v_cmp_eq_u32_e64 s[72:73], 2, v178
	v_add_f32_e32 v208, v130, v158
	v_cndmask_b32_e64 v158, v190, v197, s[64:65]
	v_cmp_eq_u32_e64 s[66:67], 2, v176
	v_cndmask_b32_e64 v195, v195, v204, s[72:73]
	v_cmp_eq_u32_e64 s[74:75], 3, v178
	v_cndmask_b32_e64 v158, v158, v203, s[66:67]
	v_cmp_eq_u32_e64 s[68:69], 3, v176
	v_cndmask_b32_e64 v199, v195, v196, s[74:75]
	v_mov_b32_e32 v200, v154
	v_mov_b32_e32 v198, v126
	v_cndmask_b32_e64 v158, v158, v205, s[68:69]
	v_pk_mul_f32 v[198:199], v[200:201], v[198:199]
	v_cmp_eq_u32_e64 s[76:77], 1, v180
	v_fma_f32 v154, v122, v158, v198
	v_add_f32_e32 v154, v154, v199
	v_add_f32_e32 v195, v130, v154
	v_cndmask_b32_e64 v154, v190, v197, s[76:77]
	v_cmp_eq_u32_e64 s[78:79], 2, v180
	v_cmp_eq_u32_e64 s[80:81], 3, v180
	v_mov_b32_e32 v198, v134
	v_cndmask_b32_e64 v154, v154, v203, s[78:79]
	v_mov_b32_e32 v199, v86
	v_mov_b32_e32 v197, v126
	v_cndmask_b32_e64 v154, v154, v205, s[80:81]
	v_pk_mul_f32 v[196:197], v[198:199], v[196:197]
	v_fma_f32 v154, v122, v154, v197
	v_add_f32_e32 v154, v196, v154
	v_add_f32_e32 v190, v130, v154
	v_mov_b32_dpp v203, v159 row_ror:15 row_mask:0xf bank_mask:0xf
	v_mov_b32_dpp v154, v95 row_ror:15 row_mask:0xf bank_mask:0xf
	v_mov_b32_dpp v205, v155 row_ror:15 row_mask:0xf bank_mask:0xf
	v_cndmask_b32_e32 v158, v154, v203, vcc
	v_mov_b32_dpp v196, v87 row_ror:15 row_mask:0xf bank_mask:0xf
	v_cndmask_b32_e64 v158, v158, v205, s[48:49]
	v_cndmask_b32_e64 v199, v158, v196, s[50:51]
	v_mov_b32_e32 v200, v95
	v_mov_b32_e32 v201, v135
	v_mov_b32_e32 v198, v127
	v_mov_b32_dpp v197, v95 row_ror:1 row_mask:0xf bank_mask:0xf
	v_pk_mul_f32 v[198:199], v[200:201], v[198:199]
	v_fma_f32 v158, v123, v197, v198
	v_mov_b32_dpp v202, v159 row_ror:1 row_mask:0xf bank_mask:0xf
	v_add_f32_e32 v158, v158, v199
	v_mov_b32_dpp v204, v155 row_ror:1 row_mask:0xf bank_mask:0xf
	v_add_f32_e32 v200, v131, v158
	v_cndmask_b32_e64 v158, v197, v202, s[52:53]
	v_mov_b32_dpp v209, v87 row_ror:1 row_mask:0xf bank_mask:0xf
	v_cndmask_b32_e64 v158, v158, v204, s[54:55]
	v_cndmask_b32_e64 v201, v158, v209, s[56:57]
	v_cndmask_b32_e64 v158, v154, v203, s[58:59]
	v_cndmask_b32_e64 v158, v158, v205, s[60:61]
	v_cndmask_b32_e64 v198, v158, v196, s[62:63]
	v_mov_b32_e32 v158, v135
	v_mov_b32_e32 v199, v127
	v_pk_mul_f32 v[158:159], v[158:159], v[198:199]
	v_cndmask_b32_e64 v154, v154, v203, s[70:71]
	v_fma_f32 v159, v123, v201, v159
	v_add_f32_e32 v158, v158, v159
	v_add_f32_e32 v198, v131, v158
	v_cndmask_b32_e64 v158, v197, v202, s[64:65]
	v_cndmask_b32_e64 v158, v158, v204, s[66:67]
	v_cndmask_b32_e64 v154, v154, v205, s[72:73]
	v_cndmask_b32_e64 v199, v158, v209, s[68:69]
	v_cndmask_b32_e64 v158, v154, v196, s[74:75]
	v_mov_b32_e32 v154, v135
	v_mov_b32_e32 v159, v127
	v_pk_mul_f32 v[154:155], v[154:155], v[158:159]
	v_ashrrev_i32_e32 v189, 31, v188
	v_fma_f32 v155, v123, v199, v155
	v_add_f32_e32 v154, v154, v155
	v_mul_f32_e32 v155, 0xbfb8aa3b, v207
	v_min_f32_e32 v155, 0x42700000, v155
	v_exp_f32_e32 v158, v155
	v_mul_f32_e32 v155, 0xbfb8aa3b, v200
	v_min_f32_e32 v155, 0x42700000, v155
	v_exp_f32_e32 v159, v155
	v_add_f32_e32 v199, v131, v154
	v_cndmask_b32_e64 v154, v197, v202, s[76:77]
	v_cndmask_b32_e64 v154, v154, v204, s[78:79]
	v_cndmask_b32_e64 v201, v154, v209, s[80:81]
	v_mov_b32_e32 v154, v135
	v_mov_b32_e32 v155, v87
	v_mov_b32_e32 v197, v127
; template <int N> __device__ __forceinline__ float dpp_ror(float v) { return __builtin_bit_cast(float, __builtin_amdgcn_update_dpp(0, __builtin_bit_cast(int, v), 0x120 + N, 0xf, 0xf, false)); }
; __device__ __forceinline__ unsigned cvt_pk_bf16(float lo, float hi) { unsigned r; asm volatile("v_cvt_pk_bf16_f32 %0, %1, %2" : "=v"(r) : "v"(lo), "v"(hi)); return r; }
;     __device__ __forceinline__ void run(const f32x4 (&acc)[2][2][4][2], const Unit& u, int wr, int wc, int fr, int fq, PG8_LAS unsigned char* lds, int buf) const {
;     ...
;                     for (int eh = 0; eh < 2; ++eh) { const int e = 2 * ep + eh;
;                         float R[4], L[4];
; #pragma unroll
;                         for (int m = 0; m < 4; ++m) { R[m] = dpp_ror<1>(acc[ai][1][m][n][e]); L[m] = dpp_ror<15>(acc[ai][1][m][n][e]); }
; #pragma unroll
;                         for (int m = 0; m < 4; ++m) {
;                             const float up = (fr == 0) ? R[m > 0 ? m - 1 : 0] : R[m];
;                             const float dn = (fr == 15) ? L[m < 3 ? m + 1 : 3] : L[m];
;                             xv[m][eh] = up * w0[n][e] + acc[ai][1][m][n][e] * w1[n][e] + dn * w2[n][e] + bb[n][e];
;                         } }
; #pragma unroll
;                     for (int m = 0; m < 4; ++m) {
;                         const float p0 = __builtin_amdgcn_exp2f(fminf(-1.4426950408889634f * xv[m][0], 60.0f)) + 1.0f, p1 = __builtin_amdgcn_exp2f(fminf(-1.4426950408889634f * xv[m][1], 60.0f)) + 1.0f;
;                         const float r = __builtin_amdgcn_rcpf(p0 * p1);
;                         const bool edge = (m == 0 && fr == 0) || (m == 3 && fr == 15);
;                         ov[m][0] = edge ? acc[ai][0][m][n][2 * ep] : xv[m][0] * (r * p1) * acc[ai][0][m][n][2 * ep];
;                         ov[m][1] = edge ? acc[ai][0][m][n][2 * ep + 1] : xv[m][1] * (r * p0) * acc[ai][0][m][n][2 * ep + 1];
;                     }
; #pragma unroll
;                     for (int m = 0; m < 4; ++m) op[m][n][ep] = cvt_pk_bf16(ov[m][0], ov[m][1]);
	v_pk_add_f32 v[158:159], v[158:159], 1.0 op_sel_hi:[1,0]
	v_pk_mul_f32 v[154:155], v[154:155], v[196:197]
	v_mul_f32_e32 v196, v158, v159
	v_rcp_f32_e32 v196, v196
	v_fma_f32 v155, v123, v201, v155
	v_add_f32_e32 v154, v154, v155
	v_add_f32_e32 v197, v131, v154
	v_mul_f32_e32 v154, v159, v196
	v_mul_f32_e32 v159, v207, v154
	v_mul_f32_e32 v154, 0xbfb8aa3b, v208
	v_mul_f32_e32 v155, 0xbfb8aa3b, v198
	v_min_f32_e32 v154, 0x42700000, v154
	v_min_f32_e32 v155, 0x42700000, v155
	v_exp_f32_e32 v154, v154
	v_exp_f32_e32 v155, v155
	v_mul_f32_e32 v159, v150, v159
	v_cndmask_b32_e64 v159, v150, v159, s[44:45]
	v_mul_f32_e32 v150, v158, v196
	v_pk_add_f32 v[154:155], v[154:155], 1.0 op_sel_hi:[1,0]
	v_mul_f32_e32 v150, v200, v150
	v_mul_f32_e32 v158, v154, v155
	v_rcp_f32_e32 v158, v158
	v_mul_f32_e32 v150, v151, v150
	v_cndmask_b32_e64 v196, v151, v150, s[44:45]
	s_add_i32 s23, s23, s83
	v_mul_f32_e32 v150, v155, v158
	v_mul_f32_e32 v150, v208, v150
	v_mul_f32_e32 v155, v146, v150
	v_mul_f32_e32 v146, 0xbfb8aa3b, v195
	v_min_f32_e32 v146, 0x42700000, v146
	v_exp_f32_e32 v150, v146
	v_mul_f32_e32 v146, 0xbfb8aa3b, v199
	v_min_f32_e32 v146, 0x42700000, v146
	v_exp_f32_e32 v151, v146
	v_mul_f32_e32 v146, v154, v158
	v_mul_f32_e32 v146, v198, v146
	v_mul_f32_e32 v154, v147, v146
	v_pk_add_f32 v[146:147], v[150:151], 1.0 op_sel_hi:[1,0]
	v_mul_f32_e32 v151, 0xbfb8aa3b, v197
	v_mul_f32_e32 v150, v146, v147
	v_rcp_f32_e32 v158, v150
	v_mul_f32_e32 v150, 0xbfb8aa3b, v190
	v_min_f32_e32 v150, 0x42700000, v150
	v_min_f32_e32 v151, 0x42700000, v151
	v_exp_f32_e32 v150, v150
	v_exp_f32_e32 v151, v151
	v_mul_f32_e32 v147, v147, v158
	v_mul_f32_e32 v147, v195, v147
	v_mul_f32_e32 v142, v142, v147
	v_pk_add_f32 v[150:151], v[150:151], 1.0 op_sel_hi:[1,0]
	v_mul_f32_e32 v146, v146, v158
	v_mul_f32_e32 v147, v150, v151
	v_rcp_f32_e32 v147, v147
	v_mul_f32_e32 v146, v199, v146
	v_mul_f32_e32 v143, v143, v146
	v_mov_b32_e32 v191, v126
	v_mul_f32_e32 v146, v151, v147
	v_mul_f32_e32 v146, v190, v146
	v_mul_f32_e32 v146, v138, v146
	v_cndmask_b32_e64 v138, v146, v138, s[42:43]
	v_mul_f32_e32 v146, v150, v147
	v_mul_f32_e32 v146, v197, v146
	v_mul_f32_e32 v146, v139, v146
	v_cndmask_b32_e64 v139, v146, v139, s[42:43]
	v_cvt_pk_bf16_f32 v150, v159, v196
	v_cvt_pk_bf16_f32 v146, v155, v154
	v_cvt_pk_bf16_f32 v142, v142, v143
	v_cvt_pk_bf16_f32 v138, v138, v139
	v_mov_b32_dpp v143, v96 row_ror:15 row_mask:0xf bank_mask:0xf
	v_mov_b32_dpp v151, v160 row_ror:15 row_mask:0xf bank_mask:0xf
	v_mov_b32_dpp v158, v156 row_ror:15 row_mask:0xf bank_mask:0xf
	v_cndmask_b32_e32 v159, v143, v151, vcc
	v_cndmask_b32_e64 v159, v159, v158, s[48:49]
	v_mov_b32_dpp v154, v88 row_ror:15 row_mask:0xf bank_mask:0xf
	v_cndmask_b32_e64 v197, v159, v154, s[50:51]
	v_mov_b32_e32 v198, v96
	v_mov_b32_e32 v199, v136
	v_mov_b32_e32 v196, v128
	v_mov_b32_dpp v139, v96 row_ror:1 row_mask:0xf bank_mask:0xf
	v_mov_b32_dpp v147, v160 row_ror:1 row_mask:0xf bank_mask:0xf
	v_pk_mul_f32 v[196:197], v[198:199], v[196:197]
	v_mov_b32_dpp v155, v156 row_ror:1 row_mask:0xf bank_mask:0xf
	v_fma_f32 v195, v124, v139, v196
	v_cndmask_b32_e64 v196, v139, v147, s[52:53]
	v_mov_b32_dpp v190, v88 row_ror:1 row_mask:0xf bank_mask:0xf
	v_cndmask_b32_e64 v196, v196, v155, s[54:55]
	v_cndmask_b32_e64 v200, v196, v190, s[56:57]
	v_cndmask_b32_e64 v196, v143, v151, s[58:59]
	v_cndmask_b32_e64 v196, v196, v158, s[60:61]
	v_add_f32_e32 v195, v195, v197
	v_cndmask_b32_e64 v197, v196, v154, s[62:63]
	v_mov_b32_e32 v198, v160
	v_mov_b32_e32 v196, v128
	v_pk_mul_f32 v[196:197], v[198:199], v[196:197]
	v_cndmask_b32_e64 v143, v143, v151, s[70:71]
	v_fma_f32 v160, v124, v200, v196
	v_add_f32_e32 v160, v160, v197
	v_add_f32_e32 v200, v132, v160
	v_cndmask_b32_e64 v160, v139, v147, s[64:65]
	v_cndmask_b32_e64 v143, v143, v158, s[72:73]
	v_cndmask_b32_e64 v160, v160, v155, s[66:67]
	v_cndmask_b32_e64 v197, v143, v154, s[74:75]
	v_mov_b32_e32 v198, v156
	v_mov_b32_e32 v196, v128
	v_cndmask_b32_e64 v160, v160, v190, s[68:69]
	v_pk_mul_f32 v[196:197], v[198:199], v[196:197]
	v_cndmask_b32_e64 v139, v139, v147, s[76:77]
	v_fma_f32 v143, v124, v160, v196
	v_add_f32_e32 v143, v143, v197
	v_cndmask_b32_e64 v139, v139, v155, s[78:79]
	v_mov_b32_e32 v196, v136
	v_mov_b32_e32 v197, v88
	v_mov_b32_e32 v155, v128
	v_cndmask_b32_e64 v139, v139, v190, s[80:81]
	v_pk_mul_f32 v[154:155], v[196:197], v[154:155]
	v_fma_f32 v139, v124, v139, v155
	v_mov_b32_dpp v151, v97 row_ror:15 row_mask:0xf bank_mask:0xf
	v_mov_b32_dpp v156, v161 row_ror:15 row_mask:0xf bank_mask:0xf
	v_add_f32_e32 v139, v154, v139
	v_mov_b32_dpp v190, v157 row_ror:15 row_mask:0xf bank_mask:0xf
	v_cndmask_b32_e32 v160, v151, v156, vcc
	v_mov_b32_dpp v154, v89 row_ror:15 row_mask:0xf bank_mask:0xf
	v_cndmask_b32_e64 v160, v160, v190, s[48:49]
	v_cndmask_b32_e64 v197, v160, v154, s[50:51]
	v_mov_b32_e32 v198, v97
	v_mov_b32_e32 v199, v137
	v_mov_b32_e32 v196, v129
	v_mov_b32_dpp v147, v97 row_ror:1 row_mask:0xf bank_mask:0xf
	v_pk_mul_f32 v[196:197], v[198:199], v[196:197]
	v_fma_f32 v160, v125, v147, v196
	v_mov_b32_dpp v155, v161 row_ror:1 row_mask:0xf bank_mask:0xf
	v_add_f32_e32 v160, v160, v197
	v_mov_b32_dpp v158, v157 row_ror:1 row_mask:0xf bank_mask:0xf
	v_add_f32_e32 v198, v133, v160
	v_cndmask_b32_e64 v160, v147, v155, s[52:53]
	v_mov_b32_dpp v201, v89 row_ror:1 row_mask:0xf bank_mask:0xf
	v_cndmask_b32_e64 v160, v160, v158, s[54:55]
	v_cndmask_b32_e64 v199, v160, v201, s[56:57]
	v_cndmask_b32_e64 v160, v151, v156, s[58:59]
	v_cndmask_b32_e64 v160, v160, v190, s[60:61]
	v_cndmask_b32_e64 v196, v160, v154, s[62:63]
	v_mov_b32_e32 v160, v137
	v_mov_b32_e32 v197, v129
; template <int N> __device__ __forceinline__ float dpp_ror(float v) { return __builtin_bit_cast(float, __builtin_amdgcn_update_dpp(0, __builtin_bit_cast(int, v), 0x120 + N, 0xf, 0xf, false)); }
; __device__ __forceinline__ unsigned cvt_pk_bf16(float lo, float hi) { unsigned r; asm volatile("v_cvt_pk_bf16_f32 %0, %1, %2" : "=v"(r) : "v"(lo), "v"(hi)); return r; }
;     __device__ __forceinline__ void run(const f32x4 (&acc)[2][2][4][2], const Unit& u, int wr, int wc, int fr, int fq, PG8_LAS unsigned char* lds, int buf) const {
;     ...
;                     for (int eh = 0; eh < 2; ++eh) { const int e = 2 * ep + eh;
;                         float R[4], L[4];
; #pragma unroll
;                         for (int m = 0; m < 4; ++m) { R[m] = dpp_ror<1>(acc[ai][1][m][n][e]); L[m] = dpp_ror<15>(acc[ai][1][m][n][e]); }
; #pragma unroll
;                         for (int m = 0; m < 4; ++m) {
;                             const float up = (fr == 0) ? R[m > 0 ? m - 1 : 0] : R[m];
;                             const float dn = (fr == 15) ? L[m < 3 ? m + 1 : 3] : L[m];
;                             xv[m][eh] = up * w0[n][e] + acc[ai][1][m][n][e] * w1[n][e] + dn * w2[n][e] + bb[n][e];
;                         } }
; #pragma unroll
;                     for (int m = 0; m < 4; ++m) {
;                         const float p0 = __builtin_amdgcn_exp2f(fminf(-1.4426950408889634f * xv[m][0], 60.0f)) + 1.0f, p1 = __builtin_amdgcn_exp2f(fminf(-1.4426950408889634f * xv[m][1], 60.0f)) + 1.0f;
;                         const float r = __builtin_amdgcn_rcpf(p0 * p1);
;                         const bool edge = (m == 0 && fr == 0) || (m == 3 && fr == 15);
;                         ov[m][0] = edge ? acc[ai][0][m][n][2 * ep] : xv[m][0] * (r * p1) * acc[ai][0][m][n][2 * ep];
;                         ov[m][1] = edge ? acc[ai][0][m][n][2 * ep + 1] : xv[m][1] * (r * p0) * acc[ai][0][m][n][2 * ep + 1];
;                     }
; #pragma unroll
;                     for (int m = 0; m < 4; ++m) op[m][n][ep] = cvt_pk_bf16(ov[m][0], ov[m][1]);
	v_pk_mul_f32 v[160:161], v[160:161], v[196:197]
	v_add_f32_e32 v195, v132, v195
	v_fma_f32 v161, v125, v199, v161
	v_add_f32_e32 v160, v160, v161
	v_add_f32_e32 v196, v133, v160
	v_cndmask_b32_e64 v160, v147, v155, s[64:65]
	v_cndmask_b32_e64 v151, v151, v156, s[70:71]
	v_cndmask_b32_e64 v160, v160, v158, s[66:67]
	v_cndmask_b32_e64 v151, v151, v190, s[72:73]
	v_cndmask_b32_e64 v147, v147, v155, s[76:77]
	v_mul_f32_e32 v155, 0xbfb8aa3b, v195
	v_cndmask_b32_e64 v197, v160, v201, s[68:69]
	v_cndmask_b32_e64 v160, v151, v154, s[74:75]
	v_mov_b32_e32 v156, v137
	v_mov_b32_e32 v161, v129
	v_min_f32_e32 v155, 0x42700000, v155
	v_pk_mul_f32 v[156:157], v[156:157], v[160:161]
	v_exp_f32_e32 v160, v155
	v_mul_f32_e32 v155, 0xbfb8aa3b, v198
	v_min_f32_e32 v155, 0x42700000, v155
	v_exp_f32_e32 v161, v155
	v_fma_f32 v151, v125, v197, v157
	v_add_f32_e32 v151, v156, v151
	v_mov_b32_e32 v156, v137
	v_mov_b32_e32 v157, v89
	v_mov_b32_e32 v155, v129
	v_pk_mul_f32 v[154:155], v[156:157], v[154:155]
	v_pk_add_f32 v[156:157], v[160:161], 1.0 op_sel_hi:[1,0]
	v_cndmask_b32_e64 v147, v147, v158, s[78:79]
	v_mul_f32_e32 v158, v156, v157
	v_rcp_f32_e32 v158, v158
	v_cndmask_b32_e64 v147, v147, v201, s[80:81]
	v_fma_f32 v147, v125, v147, v155
	v_add_f32_e32 v147, v154, v147
	v_mul_f32_e32 v154, v157, v158
	v_mul_f32_e32 v157, v195, v154
	v_mul_f32_e32 v154, 0xbfb8aa3b, v200
	v_mul_f32_e32 v155, 0xbfb8aa3b, v196
	v_min_f32_e32 v154, 0x42700000, v154
	v_min_f32_e32 v155, 0x42700000, v155
	v_exp_f32_e32 v154, v154
	v_exp_f32_e32 v155, v155
	v_mul_f32_e32 v157, v152, v157
	v_cndmask_b32_e64 v157, v152, v157, s[44:45]
	v_mul_f32_e32 v152, v156, v158
	v_pk_add_f32 v[154:155], v[154:155], 1.0 op_sel_hi:[1,0]
	v_mul_f32_e32 v152, v198, v152
	v_mul_f32_e32 v156, v154, v155
	v_rcp_f32_e32 v156, v156
	v_mul_f32_e32 v152, v153, v152
	v_cndmask_b32_e64 v158, v153, v152, s[44:45]
	v_add_f32_e32 v143, v132, v143
	v_mul_f32_e32 v152, v155, v156
	v_mul_f32_e32 v152, v200, v152
	v_mul_f32_e32 v155, v148, v152
	v_mul_f32_e32 v148, 0xbfb8aa3b, v143
	v_add_f32_e32 v151, v133, v151
	v_min_f32_e32 v148, 0x42700000, v148
	v_exp_f32_e32 v152, v148
	v_mul_f32_e32 v148, 0xbfb8aa3b, v151
	v_min_f32_e32 v148, 0x42700000, v148
	v_exp_f32_e32 v153, v148
	v_mul_f32_e32 v148, v154, v156
	v_mul_f32_e32 v148, v196, v148
	v_mul_f32_e32 v154, v149, v148
	v_pk_add_f32 v[148:149], v[152:153], 1.0 op_sel_hi:[1,0]
	v_add_f32_e32 v139, v132, v139
	v_add_f32_e32 v147, v133, v147
	v_mul_f32_e32 v152, v148, v149
	v_rcp_f32_e32 v156, v152
	v_mul_f32_e32 v152, 0xbfb8aa3b, v139
	v_mul_f32_e32 v153, 0xbfb8aa3b, v147
	v_min_f32_e32 v152, 0x42700000, v152
	v_min_f32_e32 v153, 0x42700000, v153
	v_exp_f32_e32 v152, v152
	v_exp_f32_e32 v153, v153
	v_mul_f32_e32 v149, v149, v156
	v_mul_f32_e32 v143, v143, v149
	v_mul_f32_e32 v143, v144, v143
	v_pk_add_f32 v[152:153], v[152:153], 1.0 op_sel_hi:[1,0]
	v_mul_f32_e32 v148, v148, v156
	v_mul_f32_e32 v144, v152, v153
	v_rcp_f32_e32 v144, v144
	v_mul_f32_e32 v148, v151, v148
	v_mul_f32_e32 v145, v145, v148
	v_mov_b32_e32 v159, v128
	v_mul_f32_e32 v148, v153, v144
	v_mul_f32_e32 v139, v139, v148
	v_mul_f32_e32 v139, v140, v139
	v_cndmask_b32_e64 v139, v139, v140, s[42:43]
	v_mul_f32_e32 v140, v152, v144
	v_mul_f32_e32 v140, v147, v140
	v_mul_f32_e32 v140, v141, v140
	v_cndmask_b32_e64 v140, v140, v141, s[42:43]
	v_cvt_pk_bf16_f32 v151, v157, v158
	v_cvt_pk_bf16_f32 v147, v155, v154
	v_cvt_pk_bf16_f32 v143, v143, v145
	v_cvt_pk_bf16_f32 v139, v139, v140
	v_mov_b32_dpp v152, v90 row_ror:15 row_mask:0xf bank_mask:0xf
	v_mov_b32_dpp v154, v118 row_ror:15 row_mask:0xf bank_mask:0xf
	v_mov_b32_dpp v157, v114 row_ror:15 row_mask:0xf bank_mask:0xf
	v_cndmask_b32_e32 v144, v152, v154, vcc
	v_cndmask_b32_e64 v144, v144, v157, s[48:49]
	v_mov_b32_dpp v140, v82 row_ror:15 row_mask:0xf bank_mask:0xf
	v_cndmask_b32_e64 v145, v144, v140, s[50:51]
	v_mov_b32_e32 v148, v90
	v_mov_b32_e32 v149, v78
	v_mov_b32_e32 v144, v74
	v_mov_b32_dpp v141, v90 row_ror:1 row_mask:0xf bank_mask:0xf
	v_pk_mul_f32 v[144:145], v[148:149], v[144:145]
	v_fma_f32 v144, v66, v141, v144
	v_mov_b32_dpp v153, v118 row_ror:1 row_mask:0xf bank_mask:0xf
	v_add_f32_e32 v144, v144, v145
	v_mov_b32_dpp v156, v114 row_ror:1 row_mask:0xf bank_mask:0xf
	v_add_f32_e32 v160, v70, v144
	v_cndmask_b32_e64 v144, v141, v153, s[52:53]
	v_mov_b32_dpp v158, v82 row_ror:1 row_mask:0xf bank_mask:0xf
	v_cndmask_b32_e64 v144, v144, v156, s[54:55]
	v_cndmask_b32_e64 v161, v144, v158, s[56:57]
	v_cndmask_b32_e64 v144, v152, v154, s[58:59]
	v_cndmask_b32_e64 v144, v144, v157, s[60:61]
	v_cndmask_b32_e64 v145, v144, v140, s[62:63]
	v_mov_b32_e32 v148, v118
	v_mov_b32_e32 v144, v74
	v_pk_mul_f32 v[144:145], v[148:149], v[144:145]
	v_mov_b32_e32 v148, v114
	v_fma_f32 v118, v66, v161, v144
	v_add_f32_e32 v118, v118, v145
	v_cndmask_b32_e64 v144, v152, v154, s[70:71]
	v_add_f32_e32 v161, v70, v118
	v_cndmask_b32_e64 v118, v141, v153, s[64:65]
	v_cndmask_b32_e64 v144, v144, v157, s[72:73]
	v_cndmask_b32_e64 v118, v118, v156, s[66:67]
	v_cndmask_b32_e64 v145, v144, v140, s[74:75]
	v_mov_b32_e32 v144, v74
	v_cndmask_b32_e64 v118, v118, v158, s[68:69]
	v_pk_mul_f32 v[144:145], v[148:149], v[144:145]
	v_mov_b32_e32 v148, v91
	v_fma_f32 v114, v66, v118, v144
	v_add_f32_e32 v114, v114, v145
	v_add_f32_e32 v152, v70, v114
	v_cndmask_b32_e64 v114, v141, v153, s[76:77]
	v_cndmask_b32_e64 v114, v114, v156, s[78:79]
	v_mov_b32_e32 v144, v78
	v_mov_b32_e32 v145, v82
	v_mov_b32_e32 v141, v74
	v_cndmask_b32_e64 v114, v114, v158, s[80:81]
	v_pk_mul_f32 v[140:141], v[144:145], v[140:141]
	v_fma_f32 v114, v66, v114, v141
	v_add_f32_e32 v114, v140, v114
; template <int N> __device__ __forceinline__ float dpp_ror(float v) { return __builtin_bit_cast(float, __builtin_amdgcn_update_dpp(0, __builtin_bit_cast(int, v), 0x120 + N, 0xf, 0xf, false)); }
; __device__ __forceinline__ unsigned cvt_pk_bf16(float lo, float hi) { unsigned r; asm volatile("v_cvt_pk_bf16_f32 %0, %1, %2" : "=v"(r) : "v"(lo), "v"(hi)); return r; }
;     __device__ __forceinline__ void run(const f32x4 (&acc)[2][2][4][2], const Unit& u, int wr, int wc, int fr, int fq, PG8_LAS unsigned char* lds, int buf) const {
;     ...
;                     for (int eh = 0; eh < 2; ++eh) { const int e = 2 * ep + eh;
;                         float R[4], L[4];
; #pragma unroll
;                         for (int m = 0; m < 4; ++m) { R[m] = dpp_ror<1>(acc[ai][1][m][n][e]); L[m] = dpp_ror<15>(acc[ai][1][m][n][e]); }
; #pragma unroll
;                         for (int m = 0; m < 4; ++m) {
;                             const float up = (fr == 0) ? R[m > 0 ? m - 1 : 0] : R[m];
;                             const float dn = (fr == 15) ? L[m < 3 ? m + 1 : 3] : L[m];
;                             xv[m][eh] = up * w0[n][e] + acc[ai][1][m][n][e] * w1[n][e] + dn * w2[n][e] + bb[n][e];
;                         } }
; #pragma unroll
;                     for (int m = 0; m < 4; ++m) {
;                         const float p0 = __builtin_amdgcn_exp2f(fminf(-1.4426950408889634f * xv[m][0], 60.0f)) + 1.0f, p1 = __builtin_amdgcn_exp2f(fminf(-1.4426950408889634f * xv[m][1], 60.0f)) + 1.0f;
;                         const float r = __builtin_amdgcn_rcpf(p0 * p1);
;                         const bool edge = (m == 0 && fr == 0) || (m == 3 && fr == 15);
;                         ov[m][0] = edge ? acc[ai][0][m][n][2 * ep] : xv[m][0] * (r * p1) * acc[ai][0][m][n][2 * ep];
;                         ov[m][1] = edge ? acc[ai][0][m][n][2 * ep + 1] : xv[m][1] * (r * p0) * acc[ai][0][m][n][2 * ep + 1];
;                     }
; #pragma unroll
;                     for (int m = 0; m < 4; ++m) op[m][n][ep] = cvt_pk_bf16(ov[m][0], ov[m][1]);
	v_add_f32_e32 v153, v70, v114
	v_mov_b32_dpp v156, v119 row_ror:15 row_mask:0xf bank_mask:0xf
	v_mov_b32_dpp v114, v91 row_ror:15 row_mask:0xf bank_mask:0xf
	v_mov_b32_dpp v158, v115 row_ror:15 row_mask:0xf bank_mask:0xf
	v_cndmask_b32_e32 v118, v114, v156, vcc
	v_mov_b32_dpp v140, v83 row_ror:15 row_mask:0xf bank_mask:0xf
	v_cndmask_b32_e64 v118, v118, v158, s[48:49]
	v_cndmask_b32_e64 v145, v118, v140, s[50:51]
	v_mov_b32_e32 v149, v79
	v_mov_b32_e32 v144, v75
	v_mov_b32_dpp v141, v91 row_ror:1 row_mask:0xf bank_mask:0xf
	v_pk_mul_f32 v[144:145], v[148:149], v[144:145]
	v_fma_f32 v118, v67, v141, v144
	v_mov_b32_dpp v154, v119 row_ror:1 row_mask:0xf bank_mask:0xf
	v_add_f32_e32 v118, v118, v145
	v_mov_b32_dpp v157, v115 row_ror:1 row_mask:0xf bank_mask:0xf
	v_add_f32_e32 v148, v71, v118
	v_cndmask_b32_e64 v118, v141, v154, s[52:53]
	v_mov_b32_dpp v190, v83 row_ror:1 row_mask:0xf bank_mask:0xf
	v_cndmask_b32_e64 v118, v118, v157, s[54:55]
	v_cndmask_b32_e64 v149, v118, v190, s[56:57]
	v_cndmask_b32_e64 v118, v114, v156, s[58:59]
	v_cndmask_b32_e64 v118, v118, v158, s[60:61]
	v_cndmask_b32_e64 v144, v118, v140, s[62:63]
	v_mov_b32_e32 v118, v79
	v_mov_b32_e32 v145, v75
	v_pk_mul_f32 v[118:119], v[118:119], v[144:145]
	v_cndmask_b32_e64 v114, v114, v156, s[70:71]
	v_fma_f32 v119, v67, v149, v119
	v_add_f32_e32 v118, v118, v119
	v_add_f32_e32 v144, v71, v118
	v_cndmask_b32_e64 v118, v141, v154, s[64:65]
	v_cndmask_b32_e64 v118, v118, v157, s[66:67]
	v_cndmask_b32_e64 v114, v114, v158, s[72:73]
	v_cndmask_b32_e64 v145, v118, v190, s[68:69]
	v_cndmask_b32_e64 v118, v114, v140, s[74:75]
	v_mov_b32_e32 v114, v79
	v_mov_b32_e32 v119, v75
	v_pk_mul_f32 v[114:115], v[114:115], v[118:119]
	v_mov_b32_e32 v155, v74
	v_fma_f32 v115, v67, v145, v115
	v_add_f32_e32 v114, v114, v115
	v_mul_f32_e32 v115, 0xbfb8aa3b, v160
	v_min_f32_e32 v115, 0x42700000, v115
	v_exp_f32_e32 v118, v115
	v_mul_f32_e32 v115, 0xbfb8aa3b, v148
	v_min_f32_e32 v115, 0x42700000, v115
	v_exp_f32_e32 v119, v115
	v_add_f32_e32 v145, v71, v114
	v_cndmask_b32_e64 v114, v141, v154, s[76:77]
	v_cndmask_b32_e64 v114, v114, v157, s[78:79]
	v_cndmask_b32_e64 v149, v114, v190, s[80:81]
	v_mov_b32_e32 v114, v79
	v_mov_b32_e32 v115, v83
	v_mov_b32_e32 v141, v75
	v_pk_add_f32 v[118:119], v[118:119], 1.0 op_sel_hi:[1,0]
	v_pk_mul_f32 v[114:115], v[114:115], v[140:141]
	v_mul_f32_e32 v140, v118, v119
	v_rcp_f32_e32 v140, v140
	v_fma_f32 v115, v67, v149, v115
	v_add_f32_e32 v114, v114, v115
	v_add_f32_e32 v141, v71, v114
	v_mul_f32_e32 v114, v119, v140
	v_mul_f32_e32 v119, v160, v114
	v_mul_f32_e32 v114, 0xbfb8aa3b, v161
	v_mul_f32_e32 v115, 0xbfb8aa3b, v144
	v_min_f32_e32 v114, 0x42700000, v114
	v_min_f32_e32 v115, 0x42700000, v115
	v_exp_f32_e32 v114, v114
	v_exp_f32_e32 v115, v115
	v_mul_f32_e32 v119, v110, v119
	v_cndmask_b32_e64 v119, v110, v119, s[44:45]
	v_mul_f32_e32 v110, v118, v140
	v_pk_add_f32 v[114:115], v[114:115], 1.0 op_sel_hi:[1,0]
	v_mul_f32_e32 v110, v148, v110
	v_mul_f32_e32 v118, v114, v115
	v_rcp_f32_e32 v118, v118
	v_mul_f32_e32 v110, v111, v110
	v_cndmask_b32_e64 v140, v111, v110, s[44:45]
	v_mul_f32_e32 v110, v115, v118
	v_mul_f32_e32 v110, v161, v110
	v_mul_f32_e32 v115, v106, v110
	v_mul_f32_e32 v106, 0xbfb8aa3b, v152
	v_min_f32_e32 v106, 0x42700000, v106
	v_exp_f32_e32 v110, v106
	v_mul_f32_e32 v106, 0xbfb8aa3b, v145
	v_min_f32_e32 v106, 0x42700000, v106
	v_exp_f32_e32 v111, v106
	v_mul_f32_e32 v106, v114, v118
	v_mul_f32_e32 v106, v144, v106
	v_mul_f32_e32 v114, v107, v106
	v_pk_add_f32 v[106:107], v[110:111], 1.0 op_sel_hi:[1,0]
	v_mul_f32_e32 v111, 0xbfb8aa3b, v141
	v_mul_f32_e32 v110, v106, v107
	v_rcp_f32_e32 v118, v110
	v_mul_f32_e32 v110, 0xbfb8aa3b, v153
	v_min_f32_e32 v110, 0x42700000, v110
	v_min_f32_e32 v111, 0x42700000, v111
	v_exp_f32_e32 v110, v110
	v_exp_f32_e32 v111, v111
	v_mul_f32_e32 v107, v107, v118
	v_mul_f32_e32 v107, v152, v107
	v_mul_f32_e32 v102, v102, v107
	v_pk_add_f32 v[110:111], v[110:111], 1.0 op_sel_hi:[1,0]
	v_mul_f32_e32 v106, v106, v118
	v_mul_f32_e32 v107, v110, v111
	v_rcp_f32_e32 v107, v107
	v_mul_f32_e32 v106, v145, v106
	v_mul_f32_e32 v103, v103, v106
	v_cvt_pk_bf16_f32 v152, v119, v140
	v_mul_f32_e32 v106, v111, v107
	v_mul_f32_e32 v106, v153, v106
	v_mul_f32_e32 v106, v98, v106
	v_cndmask_b32_e64 v98, v106, v98, s[42:43]
	v_mul_f32_e32 v106, v110, v107
	v_mul_f32_e32 v106, v141, v106
	v_mul_f32_e32 v106, v99, v106
	v_cndmask_b32_e64 v99, v106, v99, s[42:43]
	v_cvt_pk_bf16_f32 v148, v115, v114
	v_cvt_pk_bf16_f32 v144, v102, v103
	v_cvt_pk_bf16_f32 v140, v98, v99
	v_mov_b32_dpp v103, v92 row_ror:15 row_mask:0xf bank_mask:0xf
	v_mov_b32_dpp v115, v120 row_ror:15 row_mask:0xf bank_mask:0xf
	v_mov_b32_dpp v119, v116 row_ror:15 row_mask:0xf bank_mask:0xf
	v_cndmask_b32_e32 v99, v103, v115, vcc
	v_cndmask_b32_e64 v99, v99, v119, s[48:49]
	v_mov_b32_dpp v102, v84 row_ror:15 row_mask:0xf bank_mask:0xf
	v_cndmask_b32_e64 v107, v99, v102, s[50:51]
	v_mov_b32_e32 v110, v92
	v_mov_b32_e32 v111, v80
	v_mov_b32_e32 v106, v76
	v_mov_b32_dpp v98, v92 row_ror:1 row_mask:0xf bank_mask:0xf
	v_pk_mul_f32 v[106:107], v[110:111], v[106:107]
	v_fma_f32 v106, v68, v98, v106
	v_mov_b32_dpp v114, v120 row_ror:1 row_mask:0xf bank_mask:0xf
	v_add_f32_e32 v106, v106, v107
	v_mov_b32_dpp v118, v116 row_ror:1 row_mask:0xf bank_mask:0xf
	v_add_f32_e32 v145, v72, v106
	v_cndmask_b32_e64 v106, v98, v114, s[52:53]
	v_mov_b32_dpp v141, v84 row_ror:1 row_mask:0xf bank_mask:0xf
	v_cndmask_b32_e64 v106, v106, v118, s[54:55]
	v_cndmask_b32_e64 v149, v106, v141, s[56:57]
	v_cndmask_b32_e64 v106, v103, v115, s[58:59]
	v_cndmask_b32_e64 v106, v106, v119, s[60:61]
;     __device__ __forceinline__ void run(const f32x4 (&acc)[2][2][4][2], const Unit& u, int wr, int wc, int fr, int fq, PG8_LAS unsigned char* lds, int buf) const {
;     ...
;                     for (int eh = 0; eh < 2; ++eh) { const int e = 2 * ep + eh;
;                         float R[4], L[4];
; #pragma unroll
;                         for (int m = 0; m < 4; ++m) { R[m] = dpp_ror<1>(acc[ai][1][m][n][e]); L[m] = dpp_ror<15>(acc[ai][1][m][n][e]); }
; #pragma unroll
;                         for (int m = 0; m < 4; ++m) {
;                             const float up = (fr == 0) ? R[m > 0 ? m - 1 : 0] : R[m];
;                             const float dn = (fr == 15) ? L[m < 3 ? m + 1 : 3] : L[m];
;                             xv[m][eh] = up * w0[n][e] + acc[ai][1][m][n][e] * w1[n][e] + dn * w2[n][e] + bb[n][e];
;                         } }
; #pragma unroll
;                     for (int m = 0; m < 4; ++m) {
;                         const float p0 = __builtin_amdgcn_exp2f(fminf(-1.4426950408889634f * xv[m][0], 60.0f)) + 1.0f, p1 = __builtin_amdgcn_exp2f(fminf(-1.4426950408889634f * xv[m][1], 60.0f)) + 1.0f;
;                         const float r = __builtin_amdgcn_rcpf(p0 * p1);
;                         const bool edge = (m == 0 && fr == 0) || (m == 3 && fr == 15);
;                         ov[m][0] = edge ? acc[ai][0][m][n][2 * ep] : xv[m][0] * (r * p1) * acc[ai][0][m][n][2 * ep];
;                         ov[m][1] = edge ? acc[ai][0][m][n][2 * ep + 1] : xv[m][1] * (r * p0) * acc[ai][0][m][n][2 * ep + 1];
;                     }
; #pragma unroll
;                     for (int m = 0; m < 4; ++m) op[m][n][ep] = cvt_pk_bf16(ov[m][0], ov[m][1]);
;                     __builtin_amdgcn_sched_barrier(0);
;                 }
; #pragma unroll
;             for (int m = 0; m < 4; ++m) {
;                 u32x4 w; w.x = op[m][0][0]; w.y = op[m][0][1]; w.z = op[m][1][0]; w.w = op[m][1][1];
;                 *(u32x4*)(ACT + (size_t)(row0 + ai * HALF + m * 16) * 5632 + ch0) = w;
;             }
;             const int grp = u.pm * 4 + ai * 2 + wr;
;             if (fr <= 1) { const f32x4 g0 = acc[ai][1][0][0], g1 = acc[ai][1][0][1];
;                 u32x4 w; w.x = cvt_pk_bf16(g0[0], g0[1]); w.y = cvt_pk_bf16(g0[2], g0[3]); w.z = cvt_pk_bf16(g1[0], g1[1]); w.w = cvt_pk_bf16(g1[2], g1[3]);
;                 *(u32x4*)(GB + ((size_t)(grp * 4 + fr)) * 5632 + ch0) = w; }
	v_cndmask_b32_e64 v107, v106, v102, s[62:63]
	v_mov_b32_e32 v110, v120
	v_mov_b32_e32 v106, v76
	v_pk_mul_f32 v[106:107], v[110:111], v[106:107]
	v_cndmask_b32_e64 v103, v103, v115, s[70:71]
	v_fma_f32 v106, v68, v149, v106
	v_add_f32_e32 v106, v106, v107
	v_add_f32_e32 v149, v72, v106
	v_cndmask_b32_e64 v106, v98, v114, s[64:65]
	v_cndmask_b32_e64 v106, v106, v118, s[66:67]
	v_cndmask_b32_e64 v103, v103, v119, s[72:73]
	v_cndmask_b32_e64 v120, v106, v141, s[68:69]
	v_cndmask_b32_e64 v107, v103, v102, s[74:75]
	v_mov_b32_e32 v110, v116
	v_mov_b32_e32 v106, v76
	v_pk_mul_f32 v[106:107], v[110:111], v[106:107]
	v_cndmask_b32_e64 v98, v98, v114, s[76:77]
	v_fma_f32 v103, v68, v120, v106
	v_add_f32_e32 v103, v103, v107
	v_add_f32_e32 v115, v72, v103
	v_cndmask_b32_e64 v98, v98, v118, s[78:79]
	v_mov_b32_e32 v106, v80
	v_mov_b32_e32 v107, v84
	v_mov_b32_e32 v103, v76
	v_cndmask_b32_e64 v98, v98, v141, s[80:81]
	v_pk_mul_f32 v[102:103], v[106:107], v[102:103]
	v_fma_f32 v98, v68, v98, v103
	v_mov_b32_dpp v114, v93 row_ror:15 row_mask:0xf bank_mask:0xf
	v_mov_b32_dpp v116, v121 row_ror:15 row_mask:0xf bank_mask:0xf
	v_add_f32_e32 v98, v102, v98
	v_mov_b32_dpp v141, v117 row_ror:15 row_mask:0xf bank_mask:0xf
	v_cndmask_b32_e32 v106, v114, v116, vcc
	v_mov_b32_dpp v102, v85 row_ror:15 row_mask:0xf bank_mask:0xf
	v_cndmask_b32_e64 v106, v106, v141, s[48:49]
	v_cndmask_b32_e64 v107, v106, v102, s[50:51]
	v_mov_b32_e32 v110, v93
	v_mov_b32_e32 v111, v81
	v_mov_b32_e32 v106, v77
	v_mov_b32_dpp v103, v93 row_ror:1 row_mask:0xf bank_mask:0xf
	v_pk_mul_f32 v[106:107], v[110:111], v[106:107]
	v_fma_f32 v106, v69, v103, v106
	v_mov_b32_dpp v118, v121 row_ror:1 row_mask:0xf bank_mask:0xf
	v_add_f32_e32 v106, v106, v107
	v_mov_b32_dpp v119, v117 row_ror:1 row_mask:0xf bank_mask:0xf
	v_add_f32_e32 v154, v73, v106
	v_cndmask_b32_e64 v106, v103, v118, s[52:53]
	v_mov_b32_dpp v153, v85 row_ror:1 row_mask:0xf bank_mask:0xf
	v_cndmask_b32_e64 v106, v106, v119, s[54:55]
	v_cndmask_b32_e64 v110, v106, v153, s[56:57]
	v_cndmask_b32_e64 v106, v114, v116, s[58:59]
	v_cndmask_b32_e64 v106, v106, v141, s[60:61]
	v_cndmask_b32_e64 v106, v106, v102, s[62:63]
	v_mov_b32_e32 v120, v81
	v_mov_b32_e32 v107, v77
	v_pk_mul_f32 v[106:107], v[120:121], v[106:107]
	v_add_f32_e32 v98, v72, v98
	v_fma_f32 v107, v69, v110, v107
	v_add_f32_e32 v106, v106, v107
	v_add_f32_e32 v120, v73, v106
	v_cndmask_b32_e64 v106, v103, v118, s[64:65]
	v_cndmask_b32_e64 v106, v106, v119, s[66:67]
	v_cndmask_b32_e64 v110, v106, v153, s[68:69]
	v_cndmask_b32_e64 v106, v114, v116, s[70:71]
	v_cndmask_b32_e64 v106, v106, v141, s[72:73]
	v_cndmask_b32_e64 v103, v103, v118, s[76:77]
	v_cndmask_b32_e64 v106, v106, v102, s[74:75]
	v_mov_b32_e32 v116, v81
	v_mov_b32_e32 v107, v77
	v_cndmask_b32_e64 v103, v103, v119, s[78:79]
	v_pk_mul_f32 v[106:107], v[116:117], v[106:107]
	v_cndmask_b32_e64 v116, v103, v153, s[80:81]
	v_mul_f32_e32 v103, 0xbfb8aa3b, v145
	v_min_f32_e32 v103, 0x42700000, v103
	v_fma_f32 v107, v69, v110, v107
	v_exp_f32_e32 v110, v103
	v_mul_f32_e32 v103, 0xbfb8aa3b, v154
	v_min_f32_e32 v103, 0x42700000, v103
	v_exp_f32_e32 v111, v103
	v_add_f32_e32 v106, v106, v107
	v_add_f32_e32 v114, v73, v106
	v_mov_b32_e32 v106, v81
	v_mov_b32_e32 v107, v85
	v_mov_b32_e32 v103, v77
	v_pk_mul_f32 v[102:103], v[106:107], v[102:103]
	v_pk_add_f32 v[106:107], v[110:111], 1.0 op_sel_hi:[1,0]
	v_fma_f32 v103, v69, v116, v103
	v_mul_f32_e32 v110, v106, v107
	v_rcp_f32_e32 v110, v110
	v_add_f32_e32 v102, v102, v103
	v_add_f32_e32 v111, v73, v102
	v_mul_f32_e32 v103, 0xbfb8aa3b, v120
	v_mul_f32_e32 v102, v107, v110
	v_mul_f32_e32 v107, v145, v102
	v_mul_f32_e32 v102, 0xbfb8aa3b, v149
	v_min_f32_e32 v102, 0x42700000, v102
	v_min_f32_e32 v103, 0x42700000, v103
	v_exp_f32_e32 v102, v102
	v_exp_f32_e32 v103, v103
	v_mul_f32_e32 v107, v112, v107
	v_cndmask_b32_e64 v112, v112, v107, s[44:45]
	v_mul_f32_e32 v106, v106, v110
	v_pk_add_f32 v[102:103], v[102:103], 1.0 op_sel_hi:[1,0]
	v_mul_f32_e32 v106, v154, v106
	v_mul_f32_e32 v107, v102, v103
	v_rcp_f32_e32 v110, v107
	v_mul_f32_e32 v106, v113, v106
	v_cndmask_b32_e64 v113, v113, v106, s[44:45]
	v_mov_b32_e32 v99, v76
	v_mul_f32_e32 v103, v103, v110
	v_mul_f32_e32 v103, v149, v103
	v_mul_f32_e32 v108, v108, v103
	v_mul_f32_e32 v103, 0xbfb8aa3b, v115
	v_min_f32_e32 v103, 0x42700000, v103
	v_exp_f32_e32 v106, v103
	v_mul_f32_e32 v103, 0xbfb8aa3b, v114
	v_min_f32_e32 v103, 0x42700000, v103
	v_exp_f32_e32 v107, v103
	v_mul_f32_e32 v102, v102, v110
	v_mul_f32_e32 v102, v120, v102
	v_mul_f32_e32 v109, v109, v102
	v_pk_add_f32 v[102:103], v[106:107], 1.0 op_sel_hi:[1,0]
	v_mul_f32_e32 v107, 0xbfb8aa3b, v111
	v_mul_f32_e32 v106, v102, v103
	v_rcp_f32_e32 v110, v106
	v_mul_f32_e32 v106, 0xbfb8aa3b, v98
	v_min_f32_e32 v106, 0x42700000, v106
	v_min_f32_e32 v107, 0x42700000, v107
	v_exp_f32_e32 v106, v106
	v_exp_f32_e32 v107, v107
	v_mul_f32_e32 v103, v103, v110
	v_mul_f32_e32 v103, v115, v103
	v_mul_f32_e32 v103, v104, v103
	v_pk_add_f32 v[106:107], v[106:107], 1.0 op_sel_hi:[1,0]
	v_mul_f32_e32 v102, v102, v110
	v_mul_f32_e32 v104, v106, v107
	v_rcp_f32_e32 v104, v104
	v_mul_f32_e32 v102, v114, v102
	v_mul_f32_e32 v102, v105, v102
	v_cvt_pk_bf16_f32 v153, v112, v113
	v_mul_f32_e32 v105, v107, v104
	v_mul_f32_e32 v98, v98, v105
	v_mul_f32_e32 v98, v100, v98
	v_cndmask_b32_e64 v98, v98, v100, s[42:43]
	v_mul_f32_e32 v100, v106, v104
	v_mul_f32_e32 v100, v111, v100
	v_mul_f32_e32 v100, v101, v100
	v_cndmask_b32_e64 v100, v100, v101, s[42:43]
	v_cvt_pk_bf16_f32 v149, v108, v109
	v_cvt_pk_bf16_f32 v145, v103, v102
	v_cvt_pk_bf16_f32 v141, v98, v100
	v_mov_b64_e32 v[102:103], s[26:27]
	s_movk_i32 s31, 0x2c00
	v_mad_i64_i32 v[104:105], s[48:49], v194, s31, v[102:103]
	v_lshlrev_b64 v[100:101], 1, v[188:189]
	v_lshl_add_u64 v[104:105], v[104:105], 0, v[100:101]
	v_or_b32_e32 v98, 16, v194
	global_store_dwordx4 v[104:105], v[150:153], off
	v_mad_i64_i32 v[104:105], s[48:49], v98, s31, v[102:103]
	v_lshl_add_u64 v[104:105], v[104:105], 0, v[100:101]
	v_or_b32_e32 v98, 32, v194
	global_store_dwordx4 v[104:105], v[146:149], off
	v_mad_i64_i32 v[104:105], s[48:49], v98, s31, v[102:103]
	v_or_b32_e32 v98, 48, v194
	v_mad_i64_i32 v[102:103], s[48:49], v98, s31, v[102:103]
	v_lshl_add_u64 v[104:105], v[104:105], 0, v[100:101]
	v_lshl_add_u64 v[102:103], v[102:103], 0, v[100:101]
	global_store_dwordx4 v[104:105], v[142:145], off
	global_store_dwordx4 v[102:103], v[138:141], off
	s_and_saveexec_b64 s[48:49], s[38:39]
	s_cbranch_execz .LBB0_1164
	v_cvt_pk_bf16_f32 v94, v94, v95
	v_cvt_pk_bf16_f32 v95, v96, v97
	v_cvt_pk_bf16_f32 v96, v90, v91
	v_cvt_pk_bf16_f32 v97, v92, v93
	v_lshl_or_b32 v92, s23, 2, v21
	v_mov_b64_e32 v[90:91], s[36:37]
	v_mad_i64_i32 v[90:91], s[50:51], v92, s31, v[90:91]
	v_lshl_add_u64 v[90:91], v[188:189], 1, v[90:91]
	global_store_dwordx4 v[90:91], v[94:97], off

; template <int N> __device__ __forceinline__ float dpp_ror(float v) { return __builtin_bit_cast(float, __builtin_amdgcn_update_dpp(0, __builtin_bit_cast(int, v), 0x120 + N, 0xf, 0xf, false)); }
; __device__ __forceinline__ unsigned cvt_pk_bf16(float lo, float hi) { unsigned r; asm volatile("v_cvt_pk_bf16_f32 %0, %1, %2" : "=v"(r) : "v"(lo), "v"(hi)); return r; }
;     __device__ __forceinline__ void run(const f32x4 (&acc)[2][2][4][2], const Unit& u, int wr, int wc, int fr, int fq, PG8_LAS unsigned char* lds, int buf) const {
;     ...
;                     for (int eh = 0; eh < 2; ++eh) { const int e = 2 * ep + eh;
;                         float R[4], L[4];
; #pragma unroll
;                         for (int m = 0; m < 4; ++m) { R[m] = dpp_ror<1>(acc[ai][1][m][n][e]); L[m] = dpp_ror<15>(acc[ai][1][m][n][e]); }
; #pragma unroll
;                         for (int m = 0; m < 4; ++m) {
;                             const float up = (fr == 0) ? R[m > 0 ? m - 1 : 0] : R[m];
;                             const float dn = (fr == 15) ? L[m < 3 ? m + 1 : 3] : L[m];
;                             xv[m][eh] = up * w0[n][e] + acc[ai][1][m][n][e] * w1[n][e] + dn * w2[n][e] + bb[n][e];
;                         } }
; #pragma unroll
;                     for (int m = 0; m < 4; ++m) {
;                         const float p0 = __builtin_amdgcn_exp2f(fminf(-1.4426950408889634f * xv[m][0], 60.0f)) + 1.0f, p1 = __builtin_amdgcn_exp2f(fminf(-1.4426950408889634f * xv[m][1], 60.0f)) + 1.0f;
;                         const float r = __builtin_amdgcn_rcpf(p0 * p1);
;                         const bool edge = (m == 0 && fr == 0) || (m == 3 && fr == 15);
;                         ov[m][0] = edge ? acc[ai][0][m][n][2 * ep] : xv[m][0] * (r * p1) * acc[ai][0][m][n][2 * ep];
;                         ov[m][1] = edge ? acc[ai][0][m][n][2 * ep + 1] : xv[m][1] * (r * p0) * acc[ai][0][m][n][2 * ep + 1];
;                     }
; #pragma unroll
;                     for (int m = 0; m < 4; ++m) op[m][n][ep] = cvt_pk_bf16(ov[m][0], ov[m][1]);
.LBB0_1166:
	s_or_b64 exec, exec, s[48:49]
	s_nop 0
	v_mov_b32_dpp v87, v12 row_ror:15 row_mask:0xf bank_mask:0xf
	v_mov_b32_dpp v89, v62 row_ror:15 row_mask:0xf bank_mask:0xf
	v_cmp_ne_u64_e32 vcc, 0, v[170:171]
	v_mov_b32_dpp v91, v58 row_ror:15 row_mask:0xf bank_mask:0xf
	v_cndmask_b32_e32 v82, v87, v89, vcc
	v_cmp_eq_u32_e64 s[48:49], 2, v170
	v_mov_b32_dpp v190, v4 row_ror:15 row_mask:0xf bank_mask:0xf
	v_cmp_eq_u32_e64 s[50:51], 3, v170
	v_cndmask_b32_e64 v82, v82, v91, s[48:49]
	v_cndmask_b32_e64 v83, v82, v190, s[50:51]
	v_mov_b32_e32 v84, v12
	v_mov_b32_e32 v85, v134
	v_mov_b32_e32 v82, v126
	v_mov_b32_dpp v86, v12 row_ror:1 row_mask:0xf bank_mask:0xf
	v_pk_mul_f32 v[82:83], v[84:85], v[82:83]
	v_fma_f32 v82, v122, v86, v82
	v_mov_b32_dpp v88, v62 row_ror:1 row_mask:0xf bank_mask:0xf
	v_add_f32_e32 v82, v82, v83
	v_cmp_ne_u64_e64 s[52:53], 0, v[172:173]
	v_mov_b32_dpp v90, v58 row_ror:1 row_mask:0xf bank_mask:0xf
	v_add_f32_e32 v93, v130, v82
	v_cndmask_b32_e64 v82, v86, v88, s[52:53]
	v_cmp_eq_u32_e64 s[54:55], 2, v172
	v_mov_b32_dpp v92, v4 row_ror:1 row_mask:0xf bank_mask:0xf
	v_cmp_eq_u32_e64 s[56:57], 3, v172
	v_cndmask_b32_e64 v82, v82, v90, s[54:55]
	v_cmp_eq_u32_e64 s[58:59], 1, v174
	v_cndmask_b32_e64 v94, v82, v92, s[56:57]
	v_cmp_eq_u32_e64 s[60:61], 2, v174
	v_cndmask_b32_e64 v82, v87, v89, s[58:59]
	v_cmp_eq_u32_e64 s[62:63], 3, v174
	v_cndmask_b32_e64 v82, v82, v91, s[60:61]
	v_mov_b32_e32 v84, v62
	v_cndmask_b32_e64 v83, v82, v190, s[62:63]
	v_mov_b32_e32 v82, v126
	v_pk_mul_f32 v[82:83], v[84:85], v[82:83]
	v_cmp_eq_u32_e64 s[70:71], 1, v178
	v_fma_f32 v62, v122, v94, v82
	v_add_f32_e32 v62, v62, v83
	v_cmp_eq_u32_e64 s[64:65], 1, v176
	v_cndmask_b32_e64 v82, v87, v89, s[70:71]
	v_cmp_eq_u32_e64 s[72:73], 2, v178
	v_add_f32_e32 v94, v130, v62
	v_cndmask_b32_e64 v62, v86, v88, s[64:65]
	v_cmp_eq_u32_e64 s[66:67], 2, v176
	v_cndmask_b32_e64 v82, v82, v91, s[72:73]
	v_cmp_eq_u32_e64 s[74:75], 3, v178
	v_cndmask_b32_e64 v62, v62, v90, s[66:67]
	v_cmp_eq_u32_e64 s[68:69], 3, v176
	v_cndmask_b32_e64 v83, v82, v190, s[74:75]
	v_mov_b32_e32 v84, v58
	v_mov_b32_e32 v82, v126
	v_cndmask_b32_e64 v62, v62, v92, s[68:69]
	v_pk_mul_f32 v[82:83], v[84:85], v[82:83]
	v_cmp_eq_u32_e64 s[76:77], 1, v180
	v_fma_f32 v58, v122, v62, v82
	v_add_f32_e32 v58, v58, v83
	v_add_f32_e32 v87, v130, v58
	v_cndmask_b32_e64 v58, v86, v88, s[76:77]
	v_cmp_eq_u32_e64 s[78:79], 2, v180
	v_cmp_eq_u32_e64 s[80:81], 3, v180
	v_mov_b32_e32 v82, v134
	v_cndmask_b32_e64 v58, v58, v90, s[78:79]
	v_mov_b32_e32 v83, v4
	v_cndmask_b32_e64 v58, v58, v92, s[80:81]
	v_pk_mul_f32 v[82:83], v[82:83], v[190:191]
	v_fma_f32 v58, v122, v58, v83
	v_add_f32_e32 v58, v82, v58
	v_add_f32_e32 v86, v130, v58
	v_mov_b32_dpp v89, v63 row_ror:15 row_mask:0xf bank_mask:0xf
	v_mov_b32_dpp v58, v13 row_ror:15 row_mask:0xf bank_mask:0xf
	v_mov_b32_dpp v91, v59 row_ror:15 row_mask:0xf bank_mask:0xf
	v_cndmask_b32_e32 v62, v58, v89, vcc
	v_mov_b32_dpp v82, v5 row_ror:15 row_mask:0xf bank_mask:0xf
	v_cndmask_b32_e64 v62, v62, v91, s[48:49]
	v_cndmask_b32_e64 v85, v62, v82, s[50:51]
	v_mov_b32_e32 v134, v13
	v_mov_b32_e32 v84, v127
	v_mov_b32_dpp v83, v13 row_ror:1 row_mask:0xf bank_mask:0xf
	v_pk_mul_f32 v[84:85], v[134:135], v[84:85]
	v_fma_f32 v62, v123, v83, v84
	v_mov_b32_dpp v88, v63 row_ror:1 row_mask:0xf bank_mask:0xf
	v_add_f32_e32 v62, v62, v85
	v_mov_b32_dpp v90, v59 row_ror:1 row_mask:0xf bank_mask:0xf
	v_add_f32_e32 v84, v131, v62
	v_cndmask_b32_e64 v62, v83, v88, s[52:53]
	v_mov_b32_dpp v92, v5 row_ror:1 row_mask:0xf bank_mask:0xf
	v_cndmask_b32_e64 v62, v62, v90, s[54:55]
	v_cndmask_b32_e64 v85, v62, v92, s[56:57]
	v_cndmask_b32_e64 v62, v58, v89, s[58:59]
	v_cndmask_b32_e64 v62, v62, v91, s[60:61]
	v_cndmask_b32_e64 v126, v62, v82, s[62:63]
	v_mov_b32_e32 v62, v135
	v_pk_mul_f32 v[62:63], v[62:63], v[126:127]
	v_cndmask_b32_e64 v58, v58, v89, s[70:71]
	v_fma_f32 v63, v123, v85, v63
	v_add_f32_e32 v62, v62, v63
	v_add_f32_e32 v85, v131, v62
	v_cndmask_b32_e64 v62, v83, v88, s[64:65]
	v_cndmask_b32_e64 v58, v58, v91, s[72:73]
	v_cndmask_b32_e64 v62, v62, v90, s[66:67]
	v_cndmask_b32_e64 v126, v58, v82, s[74:75]
	v_mov_b32_e32 v58, v135
	v_cndmask_b32_e64 v62, v62, v92, s[68:69]
	v_pk_mul_f32 v[58:59], v[58:59], v[126:127]
	s_nop 0
	v_fma_f32 v59, v123, v62, v59
	v_add_f32_e32 v58, v58, v59
	v_mul_f32_e32 v59, 0xbfb8aa3b, v93
	v_min_f32_e32 v59, 0x42700000, v59
	v_exp_f32_e32 v62, v59
	v_mul_f32_e32 v59, 0xbfb8aa3b, v84
	v_min_f32_e32 v59, 0x42700000, v59
	v_exp_f32_e32 v63, v59
	v_add_f32_e32 v89, v131, v58
	v_cndmask_b32_e64 v58, v83, v88, s[76:77]
	v_cndmask_b32_e64 v58, v58, v90, s[78:79]
	v_cndmask_b32_e64 v88, v58, v92, s[80:81]
	v_mov_b32_e32 v58, v135
	v_mov_b32_e32 v59, v5
	v_mov_b32_e32 v83, v127
	v_pk_add_f32 v[62:63], v[62:63], 1.0 op_sel_hi:[1,0]
	v_pk_mul_f32 v[58:59], v[58:59], v[82:83]
	v_mul_f32_e32 v82, v62, v63
	v_rcp_f32_e32 v82, v82
	v_fma_f32 v59, v123, v88, v59
	v_add_f32_e32 v58, v58, v59
	v_add_f32_e32 v83, v131, v58
	v_mul_f32_e32 v58, v63, v82
	v_mul_f32_e32 v63, v93, v58
	v_mul_f32_e32 v58, 0xbfb8aa3b, v94
	v_mul_f32_e32 v59, 0xbfb8aa3b, v85
	v_min_f32_e32 v58, 0x42700000, v58
	v_min_f32_e32 v59, 0x42700000, v59
	v_exp_f32_e32 v58, v58
	v_exp_f32_e32 v59, v59
	v_mul_f32_e32 v63, v54, v63
	v_cndmask_b32_e64 v63, v54, v63, s[44:45]
	v_mul_f32_e32 v54, v62, v82
	v_pk_add_f32 v[58:59], v[58:59], 1.0 op_sel_hi:[1,0]
	v_mul_f32_e32 v54, v84, v54
	v_mul_f32_e32 v62, v58, v59
	v_rcp_f32_e32 v62, v62
	v_mul_f32_e32 v54, v55, v54
	v_cndmask_b32_e64 v82, v55, v54, s[44:45]
	v_mul_f32_e32 v54, v59, v62
	v_mul_f32_e32 v54, v94, v54
	v_mul_f32_e32 v59, v50, v54
; template <int N> __device__ __forceinline__ float dpp_ror(float v) { return __builtin_bit_cast(float, __builtin_amdgcn_update_dpp(0, __builtin_bit_cast(int, v), 0x120 + N, 0xf, 0xf, false)); }
; __device__ __forceinline__ unsigned cvt_pk_bf16(float lo, float hi) { unsigned r; asm volatile("v_cvt_pk_bf16_f32 %0, %1, %2" : "=v"(r) : "v"(lo), "v"(hi)); return r; }
;     __device__ __forceinline__ void run(const f32x4 (&acc)[2][2][4][2], const Unit& u, int wr, int wc, int fr, int fq, PG8_LAS unsigned char* lds, int buf) const {
;     ...
;                     for (int eh = 0; eh < 2; ++eh) { const int e = 2 * ep + eh;
;                         float R[4], L[4];
; #pragma unroll
;                         for (int m = 0; m < 4; ++m) { R[m] = dpp_ror<1>(acc[ai][1][m][n][e]); L[m] = dpp_ror<15>(acc[ai][1][m][n][e]); }
; #pragma unroll
;                         for (int m = 0; m < 4; ++m) {
;                             const float up = (fr == 0) ? R[m > 0 ? m - 1 : 0] : R[m];
;                             const float dn = (fr == 15) ? L[m < 3 ? m + 1 : 3] : L[m];
;                             xv[m][eh] = up * w0[n][e] + acc[ai][1][m][n][e] * w1[n][e] + dn * w2[n][e] + bb[n][e];
;                         } }
; #pragma unroll
;                     for (int m = 0; m < 4; ++m) {
;                         const float p0 = __builtin_amdgcn_exp2f(fminf(-1.4426950408889634f * xv[m][0], 60.0f)) + 1.0f, p1 = __builtin_amdgcn_exp2f(fminf(-1.4426950408889634f * xv[m][1], 60.0f)) + 1.0f;
;                         const float r = __builtin_amdgcn_rcpf(p0 * p1);
;                         const bool edge = (m == 0 && fr == 0) || (m == 3 && fr == 15);
;                         ov[m][0] = edge ? acc[ai][0][m][n][2 * ep] : xv[m][0] * (r * p1) * acc[ai][0][m][n][2 * ep];
;                         ov[m][1] = edge ? acc[ai][0][m][n][2 * ep + 1] : xv[m][1] * (r * p0) * acc[ai][0][m][n][2 * ep + 1];
;                     }
; #pragma unroll
;                     for (int m = 0; m < 4; ++m) op[m][n][ep] = cvt_pk_bf16(ov[m][0], ov[m][1]);
	v_mul_f32_e32 v50, 0xbfb8aa3b, v87
	v_min_f32_e32 v50, 0x42700000, v50
	v_exp_f32_e32 v54, v50
	v_mul_f32_e32 v50, 0xbfb8aa3b, v89
	v_min_f32_e32 v50, 0x42700000, v50
	v_exp_f32_e32 v55, v50
	v_mul_f32_e32 v50, v58, v62
	v_mul_f32_e32 v50, v85, v50
	v_mul_f32_e32 v58, v51, v50
	v_pk_add_f32 v[50:51], v[54:55], 1.0 op_sel_hi:[1,0]
	v_mul_f32_e32 v55, 0xbfb8aa3b, v83
	v_mul_f32_e32 v54, v50, v51
	v_rcp_f32_e32 v62, v54
	v_mul_f32_e32 v54, 0xbfb8aa3b, v86
	v_min_f32_e32 v54, 0x42700000, v54
	v_min_f32_e32 v55, 0x42700000, v55
	v_exp_f32_e32 v54, v54
	v_exp_f32_e32 v55, v55
	v_mul_f32_e32 v51, v51, v62
	v_mul_f32_e32 v51, v87, v51
	v_mul_f32_e32 v46, v46, v51
	v_pk_add_f32 v[54:55], v[54:55], 1.0 op_sel_hi:[1,0]
	v_mul_f32_e32 v50, v50, v62
	v_mul_f32_e32 v51, v54, v55
	v_rcp_f32_e32 v51, v51
	v_mul_f32_e32 v50, v89, v50
	v_mul_f32_e32 v47, v47, v50
	v_mul_f32_e32 v50, v55, v51
	v_mul_f32_e32 v50, v86, v50
	v_mul_f32_e32 v50, v42, v50
	v_cndmask_b32_e64 v42, v50, v42, s[42:43]
	v_mul_f32_e32 v50, v54, v51
	v_mul_f32_e32 v50, v83, v50
	v_mul_f32_e32 v50, v43, v50
	v_cndmask_b32_e64 v43, v50, v43, s[42:43]
	v_cvt_pk_bf16_f32 v54, v63, v82
	v_cvt_pk_bf16_f32 v50, v59, v58
	v_cvt_pk_bf16_f32 v46, v46, v47
	v_cvt_pk_bf16_f32 v42, v42, v43
	v_mov_b32_dpp v47, v14 row_ror:15 row_mask:0xf bank_mask:0xf
	v_mov_b32_dpp v55, v64 row_ror:15 row_mask:0xf bank_mask:0xf
	v_mov_b32_dpp v83, v60 row_ror:15 row_mask:0xf bank_mask:0xf
	v_cndmask_b32_e32 v58, v47, v55, vcc
	v_cndmask_b32_e64 v58, v58, v83, s[48:49]
	v_mov_b32_dpp v158, v6 row_ror:15 row_mask:0xf bank_mask:0xf
	v_cndmask_b32_e64 v59, v58, v158, s[50:51]
	v_mov_b32_e32 v62, v14
	v_mov_b32_e32 v63, v136
	v_mov_b32_e32 v58, v128
	v_mov_b32_dpp v43, v14 row_ror:1 row_mask:0xf bank_mask:0xf
	v_pk_mul_f32 v[58:59], v[62:63], v[58:59]
	v_fma_f32 v58, v124, v43, v58
	v_mov_b32_dpp v51, v64 row_ror:1 row_mask:0xf bank_mask:0xf
	v_add_f32_e32 v58, v58, v59
	v_mov_b32_dpp v82, v60 row_ror:1 row_mask:0xf bank_mask:0xf
	v_add_f32_e32 v85, v132, v58
	v_cndmask_b32_e64 v58, v43, v51, s[52:53]
	v_mov_b32_dpp v84, v6 row_ror:1 row_mask:0xf bank_mask:0xf
	v_cndmask_b32_e64 v58, v58, v82, s[54:55]
	v_cndmask_b32_e64 v86, v58, v84, s[56:57]
	v_cndmask_b32_e64 v58, v47, v55, s[58:59]
	v_cndmask_b32_e64 v58, v58, v83, s[60:61]
	v_cndmask_b32_e64 v59, v58, v158, s[62:63]
	v_mov_b32_e32 v62, v64
	v_mov_b32_e32 v58, v128
	v_pk_mul_f32 v[58:59], v[62:63], v[58:59]
	v_cndmask_b32_e64 v47, v47, v55, s[70:71]
	v_fma_f32 v58, v124, v86, v58
	v_add_f32_e32 v58, v58, v59
	v_add_f32_e32 v86, v132, v58
	v_cndmask_b32_e64 v58, v43, v51, s[64:65]
	v_cndmask_b32_e64 v58, v58, v82, s[66:67]
	v_cndmask_b32_e64 v47, v47, v83, s[72:73]
	v_cndmask_b32_e64 v64, v58, v84, s[68:69]
	v_cndmask_b32_e64 v59, v47, v158, s[74:75]
	v_mov_b32_e32 v62, v60
	v_mov_b32_e32 v58, v128
	v_pk_mul_f32 v[58:59], v[62:63], v[58:59]
	v_cndmask_b32_e64 v43, v43, v51, s[76:77]
	v_fma_f32 v47, v124, v64, v58
	v_add_f32_e32 v47, v47, v59
	v_cndmask_b32_e64 v43, v43, v82, s[78:79]
	v_mov_b32_e32 v58, v136
	v_mov_b32_e32 v59, v6
	v_cndmask_b32_e64 v43, v43, v84, s[80:81]
	v_pk_mul_f32 v[58:59], v[58:59], v[158:159]
	v_fma_f32 v43, v124, v43, v59
	v_mov_b32_dpp v55, v15 row_ror:15 row_mask:0xf bank_mask:0xf
	v_mov_b32_dpp v60, v65 row_ror:15 row_mask:0xf bank_mask:0xf
	v_add_f32_e32 v43, v58, v43
	v_mov_b32_dpp v83, v61 row_ror:15 row_mask:0xf bank_mask:0xf
	v_cndmask_b32_e32 v62, v55, v60, vcc
	v_mov_b32_dpp v58, v7 row_ror:15 row_mask:0xf bank_mask:0xf
	v_cndmask_b32_e64 v62, v62, v83, s[48:49]
	v_cndmask_b32_e64 v63, v62, v58, s[50:51]
	v_mov_b32_e32 v136, v15
	v_mov_b32_e32 v62, v129
	v_mov_b32_dpp v51, v15 row_ror:1 row_mask:0xf bank_mask:0xf
	v_pk_mul_f32 v[62:63], v[136:137], v[62:63]
	v_fma_f32 v62, v125, v51, v62
	v_mov_b32_dpp v59, v65 row_ror:1 row_mask:0xf bank_mask:0xf
	v_add_f32_e32 v62, v62, v63
	v_mov_b32_dpp v82, v61 row_ror:1 row_mask:0xf bank_mask:0xf
	v_add_f32_e32 v87, v133, v62
	v_cndmask_b32_e64 v62, v51, v59, s[52:53]
	v_mov_b32_dpp v84, v7 row_ror:1 row_mask:0xf bank_mask:0xf
	v_cndmask_b32_e64 v62, v62, v82, s[54:55]
	v_cndmask_b32_e64 v88, v62, v84, s[56:57]
	v_cndmask_b32_e64 v62, v55, v60, s[58:59]
	v_cndmask_b32_e64 v62, v62, v83, s[60:61]
	v_cndmask_b32_e64 v128, v62, v58, s[62:63]
	v_mov_b32_e32 v64, v137
	v_pk_mul_f32 v[62:63], v[64:65], v[128:129]
	v_cndmask_b32_e64 v55, v55, v60, s[70:71]
	v_fma_f32 v63, v125, v88, v63
	v_add_f32_e32 v62, v62, v63
	v_add_f32_e32 v64, v133, v62
	v_cndmask_b32_e64 v62, v51, v59, s[64:65]
	v_cndmask_b32_e64 v55, v55, v83, s[72:73]
	v_cndmask_b32_e64 v62, v62, v82, s[66:67]
	v_cndmask_b32_e64 v128, v55, v58, s[74:75]
	v_mov_b32_e32 v60, v137
	v_cndmask_b32_e64 v51, v51, v59, s[76:77]
	v_mul_f32_e32 v59, 0xbfb8aa3b, v85
	v_cndmask_b32_e64 v62, v62, v84, s[68:69]
	v_pk_mul_f32 v[60:61], v[60:61], v[128:129]
	v_min_f32_e32 v59, 0x42700000, v59
	v_fma_f32 v55, v125, v62, v61
	v_exp_f32_e32 v62, v59
	v_mul_f32_e32 v59, 0xbfb8aa3b, v87
	v_min_f32_e32 v59, 0x42700000, v59
	v_exp_f32_e32 v63, v59
	v_add_f32_e32 v55, v60, v55
	v_mov_b32_e32 v60, v137
	v_mov_b32_e32 v61, v7
	v_mov_b32_e32 v59, v129
	v_pk_mul_f32 v[58:59], v[60:61], v[58:59]
	v_pk_add_f32 v[60:61], v[62:63], 1.0 op_sel_hi:[1,0]
	v_cndmask_b32_e64 v51, v51, v82, s[78:79]
	v_mul_f32_e32 v62, v60, v61
	v_rcp_f32_e32 v62, v62
	v_cndmask_b32_e64 v51, v51, v84, s[80:81]
	v_fma_f32 v51, v125, v51, v59
	v_add_f32_e32 v51, v58, v51
	v_mul_f32_e32 v58, v61, v62
	v_mul_f32_e32 v61, v85, v58
	v_mul_f32_e32 v58, 0xbfb8aa3b, v86
	v_mul_f32_e32 v59, 0xbfb8aa3b, v64
	v_min_f32_e32 v58, 0x42700000, v58
	v_min_f32_e32 v59, 0x42700000, v59
	v_exp_f32_e32 v58, v58
; template <int N> __device__ __forceinline__ float dpp_ror(float v) { return __builtin_bit_cast(float, __builtin_amdgcn_update_dpp(0, __builtin_bit_cast(int, v), 0x120 + N, 0xf, 0xf, false)); }
; __device__ __forceinline__ unsigned cvt_pk_bf16(float lo, float hi) { unsigned r; asm volatile("v_cvt_pk_bf16_f32 %0, %1, %2" : "=v"(r) : "v"(lo), "v"(hi)); return r; }
;     __device__ __forceinline__ void run(const f32x4 (&acc)[2][2][4][2], const Unit& u, int wr, int wc, int fr, int fq, PG8_LAS unsigned char* lds, int buf) const {
;     ...
;                     for (int eh = 0; eh < 2; ++eh) { const int e = 2 * ep + eh;
;                         float R[4], L[4];
; #pragma unroll
;                         for (int m = 0; m < 4; ++m) { R[m] = dpp_ror<1>(acc[ai][1][m][n][e]); L[m] = dpp_ror<15>(acc[ai][1][m][n][e]); }
; #pragma unroll
;                         for (int m = 0; m < 4; ++m) {
;                             const float up = (fr == 0) ? R[m > 0 ? m - 1 : 0] : R[m];
;                             const float dn = (fr == 15) ? L[m < 3 ? m + 1 : 3] : L[m];
;                             xv[m][eh] = up * w0[n][e] + acc[ai][1][m][n][e] * w1[n][e] + dn * w2[n][e] + bb[n][e];
;                         } }
; #pragma unroll
;                     for (int m = 0; m < 4; ++m) {
;                         const float p0 = __builtin_amdgcn_exp2f(fminf(-1.4426950408889634f * xv[m][0], 60.0f)) + 1.0f, p1 = __builtin_amdgcn_exp2f(fminf(-1.4426950408889634f * xv[m][1], 60.0f)) + 1.0f;
;                         const float r = __builtin_amdgcn_rcpf(p0 * p1);
;                         const bool edge = (m == 0 && fr == 0) || (m == 3 && fr == 15);
;                         ov[m][0] = edge ? acc[ai][0][m][n][2 * ep] : xv[m][0] * (r * p1) * acc[ai][0][m][n][2 * ep];
;                         ov[m][1] = edge ? acc[ai][0][m][n][2 * ep + 1] : xv[m][1] * (r * p0) * acc[ai][0][m][n][2 * ep + 1];
;                     }
; #pragma unroll
;                     for (int m = 0; m < 4; ++m) op[m][n][ep] = cvt_pk_bf16(ov[m][0], ov[m][1]);
	v_exp_f32_e32 v59, v59
	v_mul_f32_e32 v61, v56, v61
	v_cndmask_b32_e64 v61, v56, v61, s[44:45]
	v_mul_f32_e32 v56, v60, v62
	v_pk_add_f32 v[58:59], v[58:59], 1.0 op_sel_hi:[1,0]
	v_mul_f32_e32 v56, v87, v56
	v_mul_f32_e32 v60, v58, v59
	v_rcp_f32_e32 v60, v60
	v_mul_f32_e32 v56, v57, v56
	v_cndmask_b32_e64 v62, v57, v56, s[44:45]
	v_add_f32_e32 v47, v132, v47
	v_mul_f32_e32 v56, v59, v60
	v_mul_f32_e32 v56, v86, v56
	v_mul_f32_e32 v59, v52, v56
	v_mul_f32_e32 v52, 0xbfb8aa3b, v47
	v_add_f32_e32 v55, v133, v55
	v_min_f32_e32 v52, 0x42700000, v52
	v_exp_f32_e32 v56, v52
	v_mul_f32_e32 v52, 0xbfb8aa3b, v55
	v_min_f32_e32 v52, 0x42700000, v52
	v_exp_f32_e32 v57, v52
	v_mul_f32_e32 v52, v58, v60
	v_mul_f32_e32 v52, v64, v52
	v_mul_f32_e32 v58, v53, v52
	v_pk_add_f32 v[52:53], v[56:57], 1.0 op_sel_hi:[1,0]
	v_add_f32_e32 v43, v132, v43
	v_add_f32_e32 v51, v133, v51
	v_mul_f32_e32 v56, v52, v53
	v_rcp_f32_e32 v60, v56
	v_mul_f32_e32 v56, 0xbfb8aa3b, v43
	v_mul_f32_e32 v57, 0xbfb8aa3b, v51
	v_min_f32_e32 v56, 0x42700000, v56
	v_min_f32_e32 v57, 0x42700000, v57
	v_exp_f32_e32 v56, v56
	v_exp_f32_e32 v57, v57
	v_mul_f32_e32 v53, v53, v60
	v_mul_f32_e32 v47, v47, v53
	v_mul_f32_e32 v47, v48, v47
	v_pk_add_f32 v[56:57], v[56:57], 1.0 op_sel_hi:[1,0]
	v_mul_f32_e32 v52, v52, v60
	v_mul_f32_e32 v48, v56, v57
	v_rcp_f32_e32 v48, v48
	v_mul_f32_e32 v52, v55, v52
	v_mul_f32_e32 v49, v49, v52
	v_cvt_pk_bf16_f32 v55, v61, v62
	v_mul_f32_e32 v52, v57, v48
	v_mul_f32_e32 v43, v43, v52
	v_mul_f32_e32 v43, v44, v43
	v_cndmask_b32_e64 v43, v43, v44, s[42:43]
	v_mul_f32_e32 v44, v56, v48
	v_mul_f32_e32 v44, v51, v44
	v_mul_f32_e32 v44, v45, v44
	v_cndmask_b32_e64 v44, v44, v45, s[42:43]
	v_cvt_pk_bf16_f32 v51, v59, v58
	v_cvt_pk_bf16_f32 v47, v47, v49
	v_cvt_pk_bf16_f32 v43, v43, v44
	v_mov_b32_dpp v53, v8 row_ror:15 row_mask:0xf bank_mask:0xf
	v_mov_b32_dpp v57, v38 row_ror:15 row_mask:0xf bank_mask:0xf
	v_mov_b32_dpp v59, v34 row_ror:15 row_mask:0xf bank_mask:0xf
	v_cndmask_b32_e32 v44, v53, v57, vcc
	v_cndmask_b32_e64 v44, v44, v59, s[48:49]
	v_mov_b32_dpp v154, v0 row_ror:15 row_mask:0xf bank_mask:0xf
	v_cndmask_b32_e64 v45, v44, v154, s[50:51]
	v_mov_b32_e32 v48, v8
	v_mov_b32_e32 v49, v78
	v_mov_b32_e32 v44, v74
	v_mov_b32_dpp v52, v8 row_ror:1 row_mask:0xf bank_mask:0xf
	v_pk_mul_f32 v[44:45], v[48:49], v[44:45]
	v_fma_f32 v44, v66, v52, v44
	v_mov_b32_dpp v56, v38 row_ror:1 row_mask:0xf bank_mask:0xf
	v_add_f32_e32 v44, v44, v45
	v_mov_b32_dpp v58, v34 row_ror:1 row_mask:0xf bank_mask:0xf
	v_add_f32_e32 v61, v70, v44
	v_cndmask_b32_e64 v44, v52, v56, s[52:53]
	v_mov_b32_dpp v60, v0 row_ror:1 row_mask:0xf bank_mask:0xf
	v_cndmask_b32_e64 v44, v44, v58, s[54:55]
	v_cndmask_b32_e64 v62, v44, v60, s[56:57]
	v_cndmask_b32_e64 v44, v53, v57, s[58:59]
	v_cndmask_b32_e64 v44, v44, v59, s[60:61]
	v_cndmask_b32_e64 v45, v44, v154, s[62:63]
	v_mov_b32_e32 v48, v38
	v_mov_b32_e32 v44, v74
	v_pk_mul_f32 v[44:45], v[48:49], v[44:45]
	v_mov_b32_e32 v48, v34
	v_fma_f32 v38, v66, v62, v44
	v_add_f32_e32 v38, v38, v45
	v_cndmask_b32_e64 v44, v53, v57, s[70:71]
	v_add_f32_e32 v62, v70, v38
	v_cndmask_b32_e64 v38, v52, v56, s[64:65]
	v_cndmask_b32_e64 v44, v44, v59, s[72:73]
	v_cndmask_b32_e64 v38, v38, v58, s[66:67]
	v_cndmask_b32_e64 v45, v44, v154, s[74:75]
	v_mov_b32_e32 v44, v74
	v_cndmask_b32_e64 v38, v38, v60, s[68:69]
	v_pk_mul_f32 v[44:45], v[48:49], v[44:45]
	v_fma_f32 v34, v66, v38, v44
	v_add_f32_e32 v34, v34, v45
	v_add_f32_e32 v53, v70, v34
	v_cndmask_b32_e64 v34, v52, v56, s[76:77]
	v_cndmask_b32_e64 v34, v34, v58, s[78:79]
	v_mov_b32_e32 v44, v78
	v_mov_b32_e32 v45, v0
	v_cndmask_b32_e64 v34, v34, v60, s[80:81]
	v_pk_mul_f32 v[44:45], v[44:45], v[154:155]
	v_mov_b32_dpp v57, v39 row_ror:15 row_mask:0xf bank_mask:0xf
	v_fma_f32 v34, v66, v34, v45
	v_add_f32_e32 v34, v44, v34
	v_add_f32_e32 v52, v70, v34
	v_mov_b32_dpp v34, v9 row_ror:15 row_mask:0xf bank_mask:0xf
	v_mov_b32_dpp v59, v35 row_ror:15 row_mask:0xf bank_mask:0xf
	v_cndmask_b32_e32 v38, v34, v57, vcc
	v_mov_b32_dpp v44, v1 row_ror:15 row_mask:0xf bank_mask:0xf
	v_cndmask_b32_e64 v38, v38, v59, s[48:49]
	v_cndmask_b32_e64 v49, v38, v44, s[50:51]
	v_mov_b32_e32 v78, v9
	v_mov_b32_e32 v48, v75
	v_mov_b32_dpp v45, v9 row_ror:1 row_mask:0xf bank_mask:0xf
	v_pk_mul_f32 v[48:49], v[78:79], v[48:49]
	v_fma_f32 v38, v67, v45, v48
	v_mov_b32_dpp v56, v39 row_ror:1 row_mask:0xf bank_mask:0xf
	v_add_f32_e32 v38, v38, v49
	v_mov_b32_dpp v58, v35 row_ror:1 row_mask:0xf bank_mask:0xf
	v_add_f32_e32 v48, v71, v38
	v_cndmask_b32_e64 v38, v45, v56, s[52:53]
	v_mov_b32_dpp v60, v1 row_ror:1 row_mask:0xf bank_mask:0xf
	v_cndmask_b32_e64 v38, v38, v58, s[54:55]
	v_cndmask_b32_e64 v49, v38, v60, s[56:57]
	v_cndmask_b32_e64 v38, v34, v57, s[58:59]
	v_cndmask_b32_e64 v38, v38, v59, s[60:61]
	v_cndmask_b32_e64 v74, v38, v44, s[62:63]
	v_mov_b32_e32 v38, v79
	v_pk_mul_f32 v[38:39], v[38:39], v[74:75]
	v_cndmask_b32_e64 v34, v34, v57, s[70:71]
	v_fma_f32 v39, v67, v49, v39
	v_add_f32_e32 v38, v38, v39
	v_add_f32_e32 v49, v71, v38
	v_cndmask_b32_e64 v38, v45, v56, s[64:65]
	v_cndmask_b32_e64 v34, v34, v59, s[72:73]
	v_cndmask_b32_e64 v38, v38, v58, s[66:67]
	v_cndmask_b32_e64 v74, v34, v44, s[74:75]
	v_mov_b32_e32 v34, v79
	v_cndmask_b32_e64 v38, v38, v60, s[68:69]
	v_pk_mul_f32 v[34:35], v[34:35], v[74:75]
	s_nop 0
	v_fma_f32 v35, v67, v38, v35
	v_add_f32_e32 v34, v34, v35
	v_mul_f32_e32 v35, 0xbfb8aa3b, v61
	v_min_f32_e32 v35, 0x42700000, v35
	v_exp_f32_e32 v38, v35
	v_mul_f32_e32 v35, 0xbfb8aa3b, v48
	v_min_f32_e32 v35, 0x42700000, v35
	v_exp_f32_e32 v39, v35
	v_add_f32_e32 v57, v71, v34
	v_cndmask_b32_e64 v34, v45, v56, s[76:77]
; template <int N> __device__ __forceinline__ float dpp_ror(float v) { return __builtin_bit_cast(float, __builtin_amdgcn_update_dpp(0, __builtin_bit_cast(int, v), 0x120 + N, 0xf, 0xf, false)); }
; __device__ __forceinline__ unsigned cvt_pk_bf16(float lo, float hi) { unsigned r; asm volatile("v_cvt_pk_bf16_f32 %0, %1, %2" : "=v"(r) : "v"(lo), "v"(hi)); return r; }
;     __device__ __forceinline__ void run(const f32x4 (&acc)[2][2][4][2], const Unit& u, int wr, int wc, int fr, int fq, PG8_LAS unsigned char* lds, int buf) const {
;     ...
;                     for (int eh = 0; eh < 2; ++eh) { const int e = 2 * ep + eh;
;                         float R[4], L[4];
; #pragma unroll
;                         for (int m = 0; m < 4; ++m) { R[m] = dpp_ror<1>(acc[ai][1][m][n][e]); L[m] = dpp_ror<15>(acc[ai][1][m][n][e]); }
; #pragma unroll
;                         for (int m = 0; m < 4; ++m) {
;                             const float up = (fr == 0) ? R[m > 0 ? m - 1 : 0] : R[m];
;                             const float dn = (fr == 15) ? L[m < 3 ? m + 1 : 3] : L[m];
;                             xv[m][eh] = up * w0[n][e] + acc[ai][1][m][n][e] * w1[n][e] + dn * w2[n][e] + bb[n][e];
;                         } }
; #pragma unroll
;                     for (int m = 0; m < 4; ++m) {
;                         const float p0 = __builtin_amdgcn_exp2f(fminf(-1.4426950408889634f * xv[m][0], 60.0f)) + 1.0f, p1 = __builtin_amdgcn_exp2f(fminf(-1.4426950408889634f * xv[m][1], 60.0f)) + 1.0f;
;                         const float r = __builtin_amdgcn_rcpf(p0 * p1);
;                         const bool edge = (m == 0 && fr == 0) || (m == 3 && fr == 15);
;                         ov[m][0] = edge ? acc[ai][0][m][n][2 * ep] : xv[m][0] * (r * p1) * acc[ai][0][m][n][2 * ep];
;                         ov[m][1] = edge ? acc[ai][0][m][n][2 * ep + 1] : xv[m][1] * (r * p0) * acc[ai][0][m][n][2 * ep + 1];
;                     }
; #pragma unroll
;                     for (int m = 0; m < 4; ++m) op[m][n][ep] = cvt_pk_bf16(ov[m][0], ov[m][1]);
	v_cndmask_b32_e64 v34, v34, v58, s[78:79]
	v_cndmask_b32_e64 v56, v34, v60, s[80:81]
	v_mov_b32_e32 v34, v79
	v_mov_b32_e32 v35, v1
	v_mov_b32_e32 v45, v75
	v_pk_add_f32 v[38:39], v[38:39], 1.0 op_sel_hi:[1,0]
	v_pk_mul_f32 v[34:35], v[34:35], v[44:45]
	v_mul_f32_e32 v44, v38, v39
	v_rcp_f32_e32 v44, v44
	v_fma_f32 v35, v67, v56, v35
	v_add_f32_e32 v34, v34, v35
	v_add_f32_e32 v45, v71, v34
	v_mul_f32_e32 v34, v39, v44
	v_mul_f32_e32 v39, v61, v34
	v_mul_f32_e32 v34, 0xbfb8aa3b, v62
	v_mul_f32_e32 v35, 0xbfb8aa3b, v49
	v_min_f32_e32 v34, 0x42700000, v34
	v_min_f32_e32 v35, 0x42700000, v35
	v_exp_f32_e32 v34, v34
	v_exp_f32_e32 v35, v35
	v_mul_f32_e32 v39, v30, v39
	v_cndmask_b32_e64 v39, v30, v39, s[44:45]
	v_mul_f32_e32 v30, v38, v44
	v_pk_add_f32 v[34:35], v[34:35], 1.0 op_sel_hi:[1,0]
	v_mul_f32_e32 v30, v48, v30
	v_mul_f32_e32 v38, v34, v35
	v_rcp_f32_e32 v38, v38
	v_mul_f32_e32 v30, v31, v30
	v_cndmask_b32_e64 v44, v31, v30, s[44:45]
	v_cvt_pk_bf16_f32 v56, v39, v44
	v_mul_f32_e32 v30, v35, v38
	v_mul_f32_e32 v30, v62, v30
	v_mul_f32_e32 v35, v26, v30
	v_mul_f32_e32 v26, 0xbfb8aa3b, v53
	v_min_f32_e32 v26, 0x42700000, v26
	v_exp_f32_e32 v30, v26
	v_mul_f32_e32 v26, 0xbfb8aa3b, v57
	v_min_f32_e32 v26, 0x42700000, v26
	v_exp_f32_e32 v31, v26
	v_mul_f32_e32 v26, v34, v38
	v_mul_f32_e32 v26, v49, v26
	v_mul_f32_e32 v34, v27, v26
	v_pk_add_f32 v[26:27], v[30:31], 1.0 op_sel_hi:[1,0]
	v_mul_f32_e32 v31, 0xbfb8aa3b, v45
	v_mul_f32_e32 v30, v26, v27
	v_rcp_f32_e32 v38, v30
	v_mul_f32_e32 v30, 0xbfb8aa3b, v52
	v_min_f32_e32 v30, 0x42700000, v30
	v_min_f32_e32 v31, 0x42700000, v31
	v_exp_f32_e32 v30, v30
	v_exp_f32_e32 v31, v31
	v_mul_f32_e32 v27, v27, v38
	v_mul_f32_e32 v27, v53, v27
	v_mul_f32_e32 v22, v22, v27
	v_pk_add_f32 v[30:31], v[30:31], 1.0 op_sel_hi:[1,0]
	v_mul_f32_e32 v26, v26, v38
	v_mul_f32_e32 v27, v30, v31
	v_rcp_f32_e32 v27, v27
	v_mul_f32_e32 v26, v57, v26
	v_mul_f32_e32 v23, v23, v26
	v_mul_f32_e32 v26, v31, v27
	v_mul_f32_e32 v26, v52, v26
	v_mul_f32_e32 v26, v16, v26
	v_cndmask_b32_e64 v16, v26, v16, s[42:43]
	v_mul_f32_e32 v26, v30, v27
	v_mul_f32_e32 v26, v45, v26
	v_mul_f32_e32 v26, v17, v26
	v_cndmask_b32_e64 v17, v26, v17, s[42:43]
	v_cvt_pk_bf16_f32 v52, v35, v34
	v_cvt_pk_bf16_f32 v48, v22, v23
	v_cvt_pk_bf16_f32 v44, v16, v17
	v_mov_b32_dpp v27, v10 row_ror:15 row_mask:0xf bank_mask:0xf
	v_mov_b32_dpp v31, v40 row_ror:15 row_mask:0xf bank_mask:0xf
	v_mov_b32_dpp v35, v36 row_ror:15 row_mask:0xf bank_mask:0xf
	v_cndmask_b32_e32 v16, v27, v31, vcc
	v_cndmask_b32_e64 v16, v16, v35, s[48:49]
	v_mov_b32_dpp v98, v2 row_ror:15 row_mask:0xf bank_mask:0xf
	v_cndmask_b32_e64 v17, v16, v98, s[50:51]
	v_mov_b32_e32 v22, v10
	v_mov_b32_e32 v23, v80
	v_mov_b32_e32 v16, v76
	v_mov_b32_dpp v26, v10 row_ror:1 row_mask:0xf bank_mask:0xf
	v_pk_mul_f32 v[16:17], v[22:23], v[16:17]
	v_fma_f32 v16, v68, v26, v16
	v_mov_b32_dpp v30, v40 row_ror:1 row_mask:0xf bank_mask:0xf
	v_add_f32_e32 v16, v16, v17
	v_mov_b32_dpp v34, v36 row_ror:1 row_mask:0xf bank_mask:0xf
	v_add_f32_e32 v39, v72, v16
	v_cndmask_b32_e64 v16, v26, v30, s[52:53]
	v_mov_b32_dpp v38, v2 row_ror:1 row_mask:0xf bank_mask:0xf
	v_cndmask_b32_e64 v16, v16, v34, s[54:55]
	v_cndmask_b32_e64 v45, v16, v38, s[56:57]
	v_cndmask_b32_e64 v16, v27, v31, s[58:59]
	v_cndmask_b32_e64 v16, v16, v35, s[60:61]
	v_cndmask_b32_e64 v17, v16, v98, s[62:63]
	v_mov_b32_e32 v22, v40
	v_mov_b32_e32 v16, v76
	v_pk_mul_f32 v[16:17], v[22:23], v[16:17]
	v_mov_b32_e32 v22, v36
	v_fma_f32 v16, v68, v45, v16
	v_add_f32_e32 v16, v16, v17
	v_add_f32_e32 v45, v72, v16
	v_cndmask_b32_e64 v16, v26, v30, s[64:65]
	v_cndmask_b32_e64 v16, v16, v34, s[66:67]
	v_cndmask_b32_e64 v40, v16, v38, s[68:69]
	v_cndmask_b32_e64 v16, v27, v31, s[70:71]
	v_cndmask_b32_e64 v16, v16, v35, s[72:73]
	v_cndmask_b32_e64 v17, v16, v98, s[74:75]
	v_mov_b32_e32 v16, v76
	v_pk_mul_f32 v[16:17], v[22:23], v[16:17]
	v_mov_b32_e32 v36, v20
	v_fma_f32 v16, v68, v40, v16
	v_add_f32_e32 v16, v16, v17
	v_add_f32_e32 v31, v72, v16
	v_cndmask_b32_e64 v16, v26, v30, s[76:77]
	v_cndmask_b32_e64 v16, v16, v34, s[78:79]
	v_cndmask_b32_e64 v22, v16, v38, s[80:81]
	v_mov_b32_e32 v16, v80
	v_mov_b32_e32 v17, v2
	v_pk_mul_f32 v[16:17], v[16:17], v[98:99]
	v_fma_f32 v17, v68, v22, v17
	v_add_f32_e32 v16, v16, v17
	v_mov_b32_dpp v26, v11 row_ror:15 row_mask:0xf bank_mask:0xf
	v_mov_b32_dpp v34, v41 row_ror:15 row_mask:0xf bank_mask:0xf
	v_add_f32_e32 v30, v72, v16
	v_mov_b32_dpp v36, v37 row_ror:15 row_mask:0xf bank_mask:0xf
	v_cndmask_b32_e32 v22, v26, v34, vcc
	v_cndmask_b32_e64 v22, v22, v36, s[48:49]
	v_mov_b32_dpp v16, v3 row_ror:15 row_mask:0xf bank_mask:0xf
	v_cndmask_b32_e64 v23, v22, v16, s[50:51]
	v_mov_b32_e32 v80, v11
	v_mov_b32_e32 v22, v77
	v_mov_b32_dpp v17, v11 row_ror:1 row_mask:0xf bank_mask:0xf
	v_pk_mul_f32 v[22:23], v[80:81], v[22:23]
	v_fma_f32 v22, v69, v17, v22
;     __device__ __forceinline__ void run(const f32x4 (&acc)[2][2][4][2], const Unit& u, int wr, int wc, int fr, int fq, PG8_LAS unsigned char* lds, int buf) const {
;     ...
;                         for (int m = 0; m < 4; ++m) { R[m] = dpp_ror<1>(acc[ai][1][m][n][e]); L[m] = dpp_ror<15>(acc[ai][1][m][n][e]); }
; #pragma unroll
;                         for (int m = 0; m < 4; ++m) {
;                             const float up = (fr == 0) ? R[m > 0 ? m - 1 : 0] : R[m];
;                             const float dn = (fr == 15) ? L[m < 3 ? m + 1 : 3] : L[m];
;                             xv[m][eh] = up * w0[n][e] + acc[ai][1][m][n][e] * w1[n][e] + dn * w2[n][e] + bb[n][e];
;                         } }
; #pragma unroll
;                     for (int m = 0; m < 4; ++m) {
;                         const float p0 = __builtin_amdgcn_exp2f(fminf(-1.4426950408889634f * xv[m][0], 60.0f)) + 1.0f, p1 = __builtin_amdgcn_exp2f(fminf(-1.4426950408889634f * xv[m][1], 60.0f)) + 1.0f;
;                         const float r = __builtin_amdgcn_rcpf(p0 * p1);
;                         const bool edge = (m == 0 && fr == 0) || (m == 3 && fr == 15);
;                         ov[m][0] = edge ? acc[ai][0][m][n][2 * ep] : xv[m][0] * (r * p1) * acc[ai][0][m][n][2 * ep];
;                         ov[m][1] = edge ? acc[ai][0][m][n][2 * ep + 1] : xv[m][1] * (r * p0) * acc[ai][0][m][n][2 * ep + 1];
;                     }
; #pragma unroll
;                     for (int m = 0; m < 4; ++m) op[m][n][ep] = cvt_pk_bf16(ov[m][0], ov[m][1]);
;                     __builtin_amdgcn_sched_barrier(0);
;                 }
; #pragma unroll
;             for (int m = 0; m < 4; ++m) {
;                 u32x4 w; w.x = op[m][0][0]; w.y = op[m][0][1]; w.z = op[m][1][0]; w.w = op[m][1][1];
;                 *(u32x4*)(ACT + (size_t)(row0 + ai * HALF + m * 16) * 5632 + ch0) = w;
;             }
;             const int grp = u.pm * 4 + ai * 2 + wr;
;             if (fr <= 1) { const f32x4 g0 = acc[ai][1][0][0], g1 = acc[ai][1][0][1];
;                 u32x4 w; w.x = cvt_pk_bf16(g0[0], g0[1]); w.y = cvt_pk_bf16(g0[2], g0[3]); w.z = cvt_pk_bf16(g1[0], g1[1]); w.w = cvt_pk_bf16(g1[2], g1[3]);
;                 *(u32x4*)(GB + ((size_t)(grp * 4 + fr)) * 5632 + ch0) = w; }
	v_mov_b32_dpp v27, v41 row_ror:1 row_mask:0xf bank_mask:0xf
	v_add_f32_e32 v22, v22, v23
	v_mov_b32_dpp v35, v37 row_ror:1 row_mask:0xf bank_mask:0xf
	v_add_f32_e32 v49, v73, v22
	v_cndmask_b32_e64 v22, v17, v27, s[52:53]
	v_mov_b32_dpp v38, v3 row_ror:1 row_mask:0xf bank_mask:0xf
	v_cndmask_b32_e64 v22, v22, v35, s[54:55]
	v_cndmask_b32_e64 v53, v22, v38, s[56:57]
	v_cndmask_b32_e64 v22, v26, v34, s[58:59]
	v_cndmask_b32_e64 v22, v22, v36, s[60:61]
	v_cndmask_b32_e64 v76, v22, v16, s[62:63]
	v_mov_b32_e32 v40, v81
	v_pk_mul_f32 v[22:23], v[40:41], v[76:77]
	s_nop 0
	v_fma_f32 v23, v69, v53, v23
	v_add_f32_e32 v22, v22, v23
	v_add_f32_e32 v40, v73, v22
	v_cndmask_b32_e64 v22, v17, v27, s[64:65]
	v_cndmask_b32_e64 v17, v17, v27, s[76:77]
	v_cndmask_b32_e64 v17, v17, v35, s[78:79]
	v_cndmask_b32_e64 v22, v22, v35, s[66:67]
	v_cndmask_b32_e64 v35, v17, v38, s[80:81]
	v_mul_f32_e32 v17, 0xbfb8aa3b, v39
	v_cndmask_b32_e64 v41, v22, v38, s[68:69]
	v_cndmask_b32_e64 v22, v26, v34, s[70:71]
	v_min_f32_e32 v17, 0x42700000, v17
	v_cndmask_b32_e64 v22, v22, v36, s[72:73]
	v_exp_f32_e32 v26, v17
	v_mul_f32_e32 v17, 0xbfb8aa3b, v49
	v_cndmask_b32_e64 v76, v22, v16, s[74:75]
	v_mov_b32_e32 v36, v81
	v_min_f32_e32 v17, 0x42700000, v17
	v_pk_mul_f32 v[22:23], v[36:37], v[76:77]
	v_exp_f32_e32 v27, v17
	v_fma_f32 v23, v69, v41, v23
	v_add_f32_e32 v22, v22, v23
	v_add_f32_e32 v34, v73, v22
	v_mov_b32_e32 v22, v81
	v_mov_b32_e32 v23, v3
	v_mov_b32_e32 v17, v77
	v_pk_mul_f32 v[16:17], v[22:23], v[16:17]
	v_pk_add_f32 v[22:23], v[26:27], 1.0 op_sel_hi:[1,0]
	v_fma_f32 v17, v69, v35, v17
	v_mul_f32_e32 v26, v22, v23
	v_rcp_f32_e32 v26, v26
	v_add_f32_e32 v16, v16, v17
	v_add_f32_e32 v27, v73, v16
	v_mul_f32_e32 v17, 0xbfb8aa3b, v40
	v_mul_f32_e32 v16, v23, v26
	v_mul_f32_e32 v23, v39, v16
	v_mul_f32_e32 v16, 0xbfb8aa3b, v45
	v_min_f32_e32 v16, 0x42700000, v16
	v_min_f32_e32 v17, 0x42700000, v17
	v_exp_f32_e32 v16, v16
	v_exp_f32_e32 v17, v17
	v_mul_f32_e32 v23, v32, v23
	v_cndmask_b32_e64 v32, v32, v23, s[44:45]
	v_mul_f32_e32 v22, v22, v26
	v_pk_add_f32 v[16:17], v[16:17], 1.0 op_sel_hi:[1,0]
	v_mul_f32_e32 v22, v49, v22
	v_mul_f32_e32 v23, v16, v17
	v_rcp_f32_e32 v26, v23
	v_mul_f32_e32 v22, v33, v22
	v_cndmask_b32_e64 v33, v33, v22, s[44:45]
	s_movk_i32 s64, 0x2c00
	v_mul_f32_e32 v17, v17, v26
	v_mul_f32_e32 v17, v45, v17
	v_mul_f32_e32 v28, v28, v17
	v_mul_f32_e32 v17, 0xbfb8aa3b, v31
	v_min_f32_e32 v17, 0x42700000, v17
	v_exp_f32_e32 v22, v17
	v_mul_f32_e32 v17, 0xbfb8aa3b, v34
	v_min_f32_e32 v17, 0x42700000, v17
	v_exp_f32_e32 v23, v17
	v_mul_f32_e32 v16, v16, v26
	v_mul_f32_e32 v16, v40, v16
	v_mul_f32_e32 v26, v29, v16
	v_pk_add_f32 v[16:17], v[22:23], 1.0 op_sel_hi:[1,0]
	v_mul_f32_e32 v23, 0xbfb8aa3b, v27
	v_mul_f32_e32 v22, v16, v17
	v_rcp_f32_e32 v29, v22
	v_mul_f32_e32 v22, 0xbfb8aa3b, v30
	v_min_f32_e32 v22, 0x42700000, v22
	v_min_f32_e32 v23, 0x42700000, v23
	v_exp_f32_e32 v22, v22
	v_exp_f32_e32 v23, v23
	v_mul_f32_e32 v17, v17, v29
	v_mul_f32_e32 v17, v31, v17
	v_mul_f32_e32 v17, v24, v17
	v_pk_add_f32 v[22:23], v[22:23], 1.0 op_sel_hi:[1,0]
	v_mul_f32_e32 v16, v16, v29
	v_mul_f32_e32 v24, v22, v23
	v_rcp_f32_e32 v24, v24
	v_mul_f32_e32 v16, v34, v16
	v_mul_f32_e32 v16, v25, v16
	v_cvt_pk_bf16_f32 v57, v32, v33
	v_mul_f32_e32 v23, v23, v24
	v_mul_f32_e32 v22, v22, v24
	v_mul_f32_e32 v23, v30, v23
	v_mul_f32_e32 v22, v27, v22
	v_mul_f32_e32 v23, v18, v23
	v_mul_f32_e32 v22, v19, v22
	v_cndmask_b32_e64 v18, v23, v18, s[42:43]
	v_cndmask_b32_e64 v19, v22, v19, s[42:43]
	v_cvt_pk_bf16_f32 v53, v28, v26
	v_cvt_pk_bf16_f32 v49, v17, v16
	v_cvt_pk_bf16_f32 v45, v18, v19
	v_add_u32_e32 v18, 0x80, v194
	v_mov_b64_e32 v[16:17], s[26:27]
	v_mad_i64_i32 v[18:19], s[48:49], v18, s64, v[16:17]
	v_lshl_add_u64 v[18:19], v[18:19], 0, v[100:101]
	global_store_dwordx4 v[18:19], v[54:57], off
	v_add_u32_e32 v18, 0x90, v194
	v_mad_i64_i32 v[18:19], s[48:49], v18, s64, v[16:17]
	v_lshl_add_u64 v[18:19], v[18:19], 0, v[100:101]
	global_store_dwordx4 v[18:19], v[50:53], off
	v_add_u32_e32 v18, 0xa0, v194
	v_mad_i64_i32 v[18:19], s[48:49], v18, s64, v[16:17]
	v_lshl_add_u64 v[18:19], v[18:19], 0, v[100:101]
	global_store_dwordx4 v[18:19], v[46:49], off
	v_add_u32_e32 v18, 0xb0, v194
	v_mad_i64_i32 v[16:17], s[48:49], v18, s64, v[16:17]
	v_lshl_add_u64 v[16:17], v[16:17], 0, v[100:101]
	s_add_i32 s23, s23, 2
	global_store_dwordx4 v[16:17], v[42:45], off
	s_and_saveexec_b64 s[48:49], s[38:39]
	s_cbranch_execz .LBB0_1169
	v_cvt_pk_bf16_f32 v12, v12, v13
	v_cvt_pk_bf16_f32 v13, v14, v15
	v_cvt_pk_bf16_f32 v14, v8, v9
	v_cvt_pk_bf16_f32 v15, v10, v11
	v_lshl_or_b32 v10, s23, 2, v21
	v_mov_b64_e32 v[8:9], s[36:37]
	v_mad_i64_i32 v[8:9], s[50:51], v10, s64, v[8:9]
	v_lshl_add_u64 v[8:9], v[188:189], 1, v[8:9]
	global_store_dwordx4 v[8:9], v[12:15], off
	s_or_b64 exec, exec, s[48:49]
	s_and_saveexec_b64 s[48:49], s[40:41]
	s_cbranch_execnz .LBB0_1170
